# cross-attention: LDS fragment reads software-pipelined (ring of 11 register quads) in 7 of 8 MFMA stages
# speedup vs baseline: 1.0823x; 1.0031x over previous
; #define LAS __attribute__((address_space(3)))
; __device__ __forceinline__ unsigned pk2(float lo, float hi) { const f32x2 v = {lo, hi}; return __builtin_bit_cast(unsigned, __builtin_convertvector(v, bf16x2_t)); }
; #define BAR_LDS() do { asm volatile("s_waitcnt lgkmcnt(0)" ::: "memory"); __builtin_amdgcn_s_barrier(); asm volatile("" ::: "memory"); } while (0)
; #define XA_PUT_V() do { _Pragma("unroll") for (int i = 0; i < 4; ++i) { const int cidx = tid + 512 * i, r = cidx >> 3, c8 = cidx & 7; *(LAS u32x2*)(Vs + r * VS + c8 * 8) = (u32x2){stg[i].x, stg[i].y}; *(LAS u32x2*)(Vs + r * VS + c8 * 8 + 4) = (u32x2){stg[i].z, stg[i].w}; } } while (0)
; __device__ __forceinline__ void xattn_phase(KA a, LAS unsigned char* lds, int G, const int tid, const int bid) {
;     ...
;         for (int kb = 0; kb < 8; ++kb) { u32x4 w; w.x = pk2(accS[2 * kb][0], accS[2 * kb][1]); w.y = pk2(accS[2 * kb][2], accS[2 * kb][3]); w.z = pk2(accS[2 * kb + 1][0], accS[2 * kb + 1][1]); w.w = pk2(accS[2 * kb + 1][2], accS[2 * kb + 1][3]); pf[kb] = __builtin_bit_cast(bf16x8, w); }
;         f32x4 accO[16];
; #pragma unroll
;         for (int n = 0; n < 16; ++n) accO[n] = (f32x4){0.f, 0.f, 0.f, 0.f};
;         const int un = u + G;
; #pragma unroll
;         for (int k4 = 0; k4 < 4; ++k4) {
;             BAR_LDS();
;             XA_PUT_V();
;             if (k4 < 3) XA_FETCH(u, 5 + k4); else if (un < 2560) XA_FETCH(un, 0);
;             BAR_LDS();
; #pragma unroll
;             for (int kb = 0; kb < 2; ++kb)
; #pragma unroll
;                 for (int dtile = 0; dtile < 16; ++dtile) {
;                     const u32x2 lo = *(const LAS u32x2*)(Vs + (16 * dtile + fr) * VS + 32 * kb + 4 * fq), hi = *(const LAS u32x2*)(Vs + (16 * dtile + fr) * VS + 32 * kb + 16 + 4 * fq);
;                     accO[dtile] = __builtin_amdgcn_mfma_f32_16x16x32_bf16(mk8(lo, hi), pf[k4 * 2 + kb], accO[dtile], 0, 0, 0);
;                 }
.LBB0_113:
	s_waitcnt lgkmcnt(0)
	s_barrier
	v_cvt_pk_bf16_f32 v88, v117, v154
	v_cvt_pk_bf16_f32 v89, v155, v156
	v_cvt_pk_bf16_f32 v90, v157, v158
	v_cvt_pk_bf16_f32 v91, v159, v182
	v_cvt_pk_bf16_f32 v0, v183, v184
	v_cvt_pk_bf16_f32 v1, v185, v186
	ds_read2_b64 v[208:211], v115 offset0:128 offset1:132
	ds_read2_b64 v[212:215], v193 offset0:128 offset1:132
	ds_read2_b64 v[216:219], v194 offset0:128 offset1:132
	ds_read2_b64 v[220:223], v195 offset0:128 offset1:132
	ds_read2_b64 v[224:227], v196 offset0:192 offset1:196
	ds_read2_b64 v[228:231], v197 offset0:208 offset1:212
	ds_read2_b64 v[232:235], v198 offset0:224 offset1:228
	s_waitcnt lgkmcnt(6)
	v_mfma_f32_16x16x32_bf16 v[4:7], v[208:211], v[88:91], v[4:7]
	v_cvt_pk_bf16_f32 v2, v187, v188
	v_cvt_pk_bf16_f32 v3, v189, v190
	v_add_f32_e32 v92, v191, v192
	v_mov_b32_e32 v117, v19
	s_add_i32 s17, s17, s74
	ds_read2_b64 v[236:239], v199 offset0:240 offset1:244
	s_waitcnt lgkmcnt(6)
	v_mfma_f32_16x16x32_bf16 v[32:35], v[212:215], v[88:91], v[32:35]
	s_add_i32 s16, s16, s74
	s_cmpk_gt_i32 s17, 0x9ff
	s_mov_b32 s18, s21
	s_mov_b32 s19, s20
	ds_read2_b64 v[240:243], v200 offset1:4
	s_waitcnt lgkmcnt(6)
	v_mfma_f32_16x16x32_bf16 v[28:31], v[216:219], v[88:91], v[28:31]
	ds_read2_b64 v[244:247], v201 offset0:16 offset1:20
	s_waitcnt lgkmcnt(6)
	v_mfma_f32_16x16x32_bf16 v[36:39], v[220:223], v[88:91], v[36:39]
	ds_read2_b64 v[248:251], v202 offset0:32 offset1:36
	s_waitcnt lgkmcnt(6)
	v_mfma_f32_16x16x32_bf16 v[40:43], v[224:227], v[88:91], v[40:43]
	ds_read2_b64 v[208:211], v203 offset0:48 offset1:52
	s_waitcnt lgkmcnt(6)
	v_mfma_f32_16x16x32_bf16 v[44:47], v[228:231], v[88:91], v[44:47]
	ds_read2_b64 v[212:215], v204 offset0:64 offset1:68
	s_waitcnt lgkmcnt(6)
	v_mfma_f32_16x16x32_bf16 v[48:51], v[232:235], v[88:91], v[48:51]
	ds_read2_b64 v[216:219], v205 offset0:80 offset1:84
	s_waitcnt lgkmcnt(6)
	v_mfma_f32_16x16x32_bf16 v[52:55], v[236:239], v[88:91], v[52:55]
	ds_read2_b64 v[220:223], v206 offset0:96 offset1:100
	s_waitcnt lgkmcnt(6)
	v_mfma_f32_16x16x32_bf16 v[56:59], v[240:243], v[88:91], v[56:59]
	ds_read2_b64 v[224:227], v143 offset1:4
	s_waitcnt lgkmcnt(6)
	v_mfma_f32_16x16x32_bf16 v[60:63], v[244:247], v[88:91], v[60:63]
	ds_read2_b64 v[228:231], v115 offset0:136 offset1:140
	s_waitcnt lgkmcnt(6)
	v_mfma_f32_16x16x32_bf16 v[64:67], v[248:251], v[88:91], v[64:67]
	ds_read2_b64 v[232:235], v193 offset0:136 offset1:140
	s_waitcnt lgkmcnt(6)
	v_mfma_f32_16x16x32_bf16 v[68:71], v[208:211], v[88:91], v[68:71]
	ds_read2_b64 v[236:239], v194 offset0:136 offset1:140
	s_waitcnt lgkmcnt(6)
	v_mfma_f32_16x16x32_bf16 v[72:75], v[212:215], v[88:91], v[72:75]
	ds_read2_b64 v[240:243], v195 offset0:136 offset1:140
	s_waitcnt lgkmcnt(6)
	v_mfma_f32_16x16x32_bf16 v[76:79], v[216:219], v[88:91], v[76:79]
	ds_read2_b64 v[244:247], v196 offset0:200 offset1:204
	s_waitcnt lgkmcnt(6)
	v_mfma_f32_16x16x32_bf16 v[80:83], v[220:223], v[88:91], v[80:83]
	ds_read2_b64 v[248:251], v197 offset0:216 offset1:220
	s_waitcnt lgkmcnt(6)
	v_mfma_f32_16x16x32_bf16 v[84:87], v[224:227], v[88:91], v[84:87]
	ds_read2_b64 v[208:211], v198 offset0:232 offset1:236
	s_waitcnt lgkmcnt(6)
	v_mfma_f32_16x16x32_bf16 v[88:91], v[228:231], v[0:3], v[4:7]
	s_nop 2
	ds_read2_b64 v[212:215], v199 offset0:248 offset1:252
	s_waitcnt lgkmcnt(6)
	v_mfma_f32_16x16x32_bf16 v[32:35], v[232:235], v[0:3], v[32:35]
	ds_read2_b64 v[216:219], v200 offset0:8 offset1:12
	s_waitcnt lgkmcnt(6)
	v_mfma_f32_16x16x32_bf16 v[94:97], v[236:239], v[0:3], v[28:31]
	s_nop 1
	ds_read2_b64 v[220:223], v201 offset0:24 offset1:28
	s_waitcnt lgkmcnt(6)
	v_mfma_f32_16x16x32_bf16 v[36:39], v[240:243], v[0:3], v[36:39]
	ds_read2_b64 v[224:227], v202 offset0:40 offset1:44
	s_waitcnt lgkmcnt(6)
	v_mfma_f32_16x16x32_bf16 v[40:43], v[244:247], v[0:3], v[40:43]
	ds_read2_b64 v[228:231], v203 offset0:56 offset1:60
	s_waitcnt lgkmcnt(6)
	v_mfma_f32_16x16x32_bf16 v[44:47], v[248:251], v[0:3], v[44:47]
	ds_read2_b64 v[232:235], v204 offset0:72 offset1:76
	s_waitcnt lgkmcnt(6)
	v_mfma_f32_16x16x32_bf16 v[48:51], v[208:211], v[0:3], v[48:51]
	ds_read2_b64 v[236:239], v205 offset0:88 offset1:92
	s_waitcnt lgkmcnt(6)
	v_mfma_f32_16x16x32_bf16 v[52:55], v[212:215], v[0:3], v[52:55]
	ds_read2_b64 v[240:243], v206 offset0:104 offset1:108
	s_waitcnt lgkmcnt(6)
	v_mfma_f32_16x16x32_bf16 v[4:7], v[216:219], v[0:3], v[56:59]
	s_nop 2
	ds_read2_b64 v[244:247], v144 offset1:4
	s_waitcnt lgkmcnt(6)
	v_mfma_f32_16x16x32_bf16 v[28:31], v[220:223], v[0:3], v[60:63]
	s_nop 2
	s_waitcnt lgkmcnt(5)
	v_mfma_f32_16x16x32_bf16 v[56:59], v[224:227], v[0:3], v[64:67]
	s_nop 2
	s_waitcnt lgkmcnt(4)
	v_mfma_f32_16x16x32_bf16 v[60:63], v[228:231], v[0:3], v[68:71]
	s_nop 2
	s_waitcnt lgkmcnt(3)
	v_mfma_f32_16x16x32_bf16 v[64:67], v[232:235], v[0:3], v[72:75]
	s_nop 2
	s_waitcnt lgkmcnt(2)
	v_mfma_f32_16x16x32_bf16 v[68:71], v[236:239], v[0:3], v[76:79]
	s_nop 2
	s_waitcnt lgkmcnt(1)
	v_mfma_f32_16x16x32_bf16 v[72:75], v[240:243], v[0:3], v[80:83]
	s_waitcnt lgkmcnt(0)
; __device__ __forceinline__ unsigned pk2(float lo, float hi) { const f32x2 v = {lo, hi}; return __builtin_bit_cast(unsigned, __builtin_convertvector(v, bf16x2_t)); }
; #define BAR_LDS() do { asm volatile("s_waitcnt lgkmcnt(0)" ::: "memory"); __builtin_amdgcn_s_barrier(); asm volatile("" ::: "memory"); } while (0)
; #define XA_PUT_K() do { _Pragma("unroll") for (int i = 0; i < 4; ++i) { const int cidx = tid + 512 * i, r = cidx >> 5, c8 = cidx & 31; *(LAS u32x4*)(Ks + r * KS + c8 * 8) = stg[i]; } } while (0)
; __device__ __forceinline__ void xattn_phase(KA a, LAS unsigned char* lds, int G, const int tid, const int bid) {
;     ...
;     for (int u = bid; u < 2560; u += G) {
;         const int qt = u >> 2, h = u & 3, row0 = qt * 128;
;         const int qrow = row0 + 16 * wid + fr;
;         bf16x8 qf[8];
; #pragma unroll
;         for (int ks = 0; ks < 8; ++ks) qf[ks] = __builtin_nontemporal_load((const bf16x8*)(Q + (size_t)qrow * 1024 + h * 256 + 32 * ks + 8 * fq));
;         f32x4 accS[16];
; #pragma unroll
;         for (int n = 0; n < 16; ++n) accS[n] = (f32x4){0.f, 0.f, 0.f, 0.f};
; #pragma unroll
;         for (int kt = 0; kt < 4; ++kt) {
;             BAR_LDS();
;             XA_PUT_K();
;             XA_FETCH(u, kt + 1);
;             BAR_LDS();
;     ...
;                     accO[dtile] = __builtin_amdgcn_mfma_f32_16x16x32_bf16(mk8(lo, hi), pf[k4 * 2 + kb], accO[dtile], 0, 0, 0);
;                 }
;         }
;         bf16_t* orow = OB + (size_t)qrow * 1024 + h * 256 + 4 * fq;
; #pragma unroll
;         for (int dtile = 0; dtile < 16; ++dtile) { u32x2 w; w.x = pk2(accO[dtile][0] * inv, accO[dtile][1] * inv); w.y = pk2(accO[dtile][2] * inv, accO[dtile][3] * inv); *(u32x2*)(orow + 16 * dtile) = w; }
	v_mfma_f32_16x16x32_bf16 v[0:3], v[244:247], v[0:3], v[84:87]
	v_rcp_f32_e32 v76, v92
	v_lshl_add_u64 v[78:79], s[8:9], 0, v[118:119]
	v_lshl_add_u64 v[78:79], v[78:79], 0, s[30:31]
	v_lshl_add_u64 v[78:79], v[78:79], 0, v[116:117]
	v_pk_mul_f32 v[32:33], v[76:77], v[32:33] op_sel_hi:[0,1]
	v_pk_mul_f32 v[34:35], v[76:77], v[34:35] op_sel_hi:[0,1]
	v_pk_mul_f32 v[4:5], v[76:77], v[4:5] op_sel_hi:[0,1]
	v_pk_mul_f32 v[6:7], v[76:77], v[6:7] op_sel_hi:[0,1]
	v_cvt_pk_bf16_f32 v32, v32, v33
	v_cvt_pk_bf16_f32 v33, v34, v35
	v_cvt_pk_bf16_f32 v4, v4, v5
	v_cvt_pk_bf16_f32 v5, v6, v7
	global_store_dwordx2 v[78:79], v[32:33], off offset:32
	v_pk_mul_f32 v[32:33], v[76:77], v[94:95] op_sel_hi:[0,1]
	v_pk_mul_f32 v[34:35], v[76:77], v[96:97] op_sel_hi:[0,1]
	global_store_dwordx2 v[78:79], v[4:5], off offset:256
	v_pk_mul_f32 v[4:5], v[76:77], v[28:29] op_sel_hi:[0,1]
	v_pk_mul_f32 v[6:7], v[76:77], v[30:31] op_sel_hi:[0,1]
	v_cvt_pk_bf16_f32 v32, v32, v33
	v_cvt_pk_bf16_f32 v33, v34, v35
	v_cvt_pk_bf16_f32 v4, v4, v5
	v_cvt_pk_bf16_f32 v5, v6, v7
	global_store_dwordx2 v[78:79], v[32:33], off offset:64
	v_pk_mul_f32 v[32:33], v[76:77], v[36:37] op_sel_hi:[0,1]
	v_pk_mul_f32 v[34:35], v[76:77], v[38:39] op_sel_hi:[0,1]
	global_store_dwordx2 v[78:79], v[4:5], off offset:288
	v_pk_mul_f32 v[4:5], v[76:77], v[56:57] op_sel_hi:[0,1]
	v_pk_mul_f32 v[6:7], v[76:77], v[58:59] op_sel_hi:[0,1]
	v_cvt_pk_bf16_f32 v32, v32, v33
	v_cvt_pk_bf16_f32 v33, v34, v35
	v_cvt_pk_bf16_f32 v4, v4, v5
	v_cvt_pk_bf16_f32 v5, v6, v7
	global_store_dwordx2 v[78:79], v[32:33], off offset:96
	v_pk_mul_f32 v[32:33], v[76:77], v[40:41] op_sel_hi:[0,1]
	v_pk_mul_f32 v[34:35], v[76:77], v[42:43] op_sel_hi:[0,1]
	global_store_dwordx2 v[78:79], v[4:5], off offset:320
	v_pk_mul_f32 v[4:5], v[76:77], v[60:61] op_sel_hi:[0,1]
	v_pk_mul_f32 v[6:7], v[76:77], v[62:63] op_sel_hi:[0,1]
	v_cvt_pk_bf16_f32 v32, v32, v33
	v_cvt_pk_bf16_f32 v33, v34, v35
	v_cvt_pk_bf16_f32 v4, v4, v5
	v_cvt_pk_bf16_f32 v5, v6, v7
	global_store_dwordx2 v[78:79], v[32:33], off offset:128
	v_pk_mul_f32 v[32:33], v[76:77], v[44:45] op_sel_hi:[0,1]
	v_pk_mul_f32 v[34:35], v[76:77], v[46:47] op_sel_hi:[0,1]
	global_store_dwordx2 v[78:79], v[4:5], off offset:352
	v_pk_mul_f32 v[4:5], v[76:77], v[64:65] op_sel_hi:[0,1]
	v_pk_mul_f32 v[6:7], v[76:77], v[66:67] op_sel_hi:[0,1]
	v_cvt_pk_bf16_f32 v32, v32, v33
	v_cvt_pk_bf16_f32 v33, v34, v35
	v_cvt_pk_bf16_f32 v4, v4, v5
	v_cvt_pk_bf16_f32 v5, v6, v7
	global_store_dwordx2 v[78:79], v[32:33], off offset:160
	v_pk_mul_f32 v[32:33], v[76:77], v[48:49] op_sel_hi:[0,1]
	v_pk_mul_f32 v[34:35], v[76:77], v[50:51] op_sel_hi:[0,1]
	global_store_dwordx2 v[78:79], v[4:5], off offset:384
	v_pk_mul_f32 v[4:5], v[76:77], v[68:69] op_sel_hi:[0,1]
	v_pk_mul_f32 v[6:7], v[76:77], v[70:71] op_sel_hi:[0,1]
	v_cvt_pk_bf16_f32 v32, v32, v33
	v_cvt_pk_bf16_f32 v33, v34, v35
	v_cvt_pk_bf16_f32 v4, v4, v5
	v_cvt_pk_bf16_f32 v5, v6, v7
	v_pk_mul_f32 v[80:81], v[76:77], v[88:89] op_sel_hi:[0,1]
	v_pk_mul_f32 v[82:83], v[76:77], v[90:91] op_sel_hi:[0,1]
	global_store_dwordx2 v[78:79], v[32:33], off offset:192
	v_pk_mul_f32 v[32:33], v[76:77], v[52:53] op_sel_hi:[0,1]
	v_pk_mul_f32 v[34:35], v[76:77], v[54:55] op_sel_hi:[0,1]
	global_store_dwordx2 v[78:79], v[4:5], off offset:416
	v_pk_mul_f32 v[4:5], v[76:77], v[72:73] op_sel_hi:[0,1]
	v_pk_mul_f32 v[6:7], v[76:77], v[74:75] op_sel_hi:[0,1]
	v_pk_mul_f32 v[0:1], v[76:77], v[0:1] op_sel_hi:[0,1]
	v_pk_mul_f32 v[2:3], v[76:77], v[2:3] op_sel_hi:[0,1]
	v_cvt_pk_bf16_f32 v80, v80, v81
	v_cvt_pk_bf16_f32 v81, v82, v83
	v_cvt_pk_bf16_f32 v32, v32, v33
	v_cvt_pk_bf16_f32 v33, v34, v35
	v_cvt_pk_bf16_f32 v4, v4, v5
	v_cvt_pk_bf16_f32 v5, v6, v7
	v_cvt_pk_bf16_f32 v0, v0, v1
	v_cvt_pk_bf16_f32 v1, v2, v3
	global_store_dwordx2 v[78:79], v[80:81], off
	global_store_dwordx2 v[78:79], v[32:33], off offset:224
	global_store_dwordx2 v[78:79], v[4:5], off offset:448
	global_store_dwordx2 v[78:79], v[0:1], off offset:480
	s_cbranch_scc1 .LBB0_118
.LBB0_114:
	s_and_b32 s10, s18, 0xffffff80
	v_add_u32_e32 v0, s10, v133
	v_ashrrev_i32_e32 v1, 31, v0
	v_lshlrev_b64 v[118:119], 11, v[0:1]
	s_and_b32 s20, s19, 0x300
	v_lshl_add_u64 v[0:1], s[2:3], 0, v[118:119]
	s_lshl_b32 s30, s20, 1
	v_lshl_add_u64 v[0:1], v[0:1], 0, s[30:31]
	v_lshl_add_u64 v[0:1], v[0:1], 0, v[18:19]
	global_load_dwordx4 v[48:51], v[0:1], off nt
	global_load_dwordx4 v[44:47], v[0:1], off offset:64 nt
	global_load_dwordx4 v[40:43], v[0:1], off offset:128 nt
	global_load_dwordx4 v[36:39], v[0:1], off offset:192 nt
	global_load_dwordx4 v[32:35], v[0:1], off offset:256 nt
	global_load_dwordx4 v[28:31], v[0:1], off offset:320 nt
	global_load_dwordx4 v[4:7], v[0:1], off offset:384 nt
	s_nop 0
	global_load_dwordx4 v[0:3], v[0:1], off offset:448 nt
	s_ashr_i32 s21, s18, 31
	s_add_i32 s11, s18, 0xffffc000
	s_lshr_b32 s21, s21, 21
	s_lshr_b32 s11, s11, 12
	s_add_i32 s21, s10, s21
	s_add_i32 s11, s11, 8
	s_ashr_i32 s21, s21, 11
	s_cmpk_lt_i32 s10, 0x4000
	s_cselect_b32 s10, s21, s11
	s_lshl_b32 s10, s10, 8
	s_or_b32 s11, s10, 64
	s_waitcnt lgkmcnt(0)
	s_barrier
	s_waitcnt vmcnt(8)
	ds_write_b128 v145, v[20:23]
	ds_write_b128 v146, v[24:27]
	ds_write_b128 v147, v[8:11]
	ds_write_b128 v148, v[12:15]
	v_add_u32_e32 v8, s11, v128
	v_ashrrev_i32_e32 v9, 31, v8
	v_lshl_add_u64 v[84:85], v[16:17], 0, s[30:31]
	v_lshlrev_b64 v[8:9], 11, v[8:9]
	v_lshl_add_u64 v[8:9], v[84:85], 0, v[8:9]
	global_load_dwordx4 v[24:27], v[8:9], off
	v_add_u32_e32 v8, s11, v129
	v_ashrrev_i32_e32 v9, 31, v8
	v_lshlrev_b64 v[8:9], 11, v[8:9]
	v_lshl_add_u64 v[8:9], v[84:85], 0, v[8:9]
	global_load_dwordx4 v[52:55], v[8:9], off
	v_add_u32_e32 v8, s11, v130
	v_ashrrev_i32_e32 v9, 31, v8
	v_lshlrev_b64 v[8:9], 11, v[8:9]
	v_lshl_add_u64 v[8:9], v[84:85], 0, v[8:9]
	global_load_dwordx4 v[56:59], v[8:9], off
	v_add_u32_e32 v8, s11, v131
	v_ashrrev_i32_e32 v9, 31, v8
	v_lshlrev_b64 v[8:9], 11, v[8:9]
	v_lshl_add_u64 v[8:9], v[84:85], 0, v[8:9]
	global_load_dwordx4 v[60:63], v[8:9], off
	s_waitcnt lgkmcnt(0)
	s_barrier
; #define LAS __attribute__((address_space(3)))
; #define BAR_LDS() do { asm volatile("s_waitcnt lgkmcnt(0)" ::: "memory"); __builtin_amdgcn_s_barrier(); asm volatile("" ::: "memory"); } while (0)
; #define XA_PUT_K() do { _Pragma("unroll") for (int i = 0; i < 4; ++i) { const int cidx = tid + 512 * i, r = cidx >> 5, c8 = cidx & 31; *(LAS u32x4*)(Ks + r * KS + c8 * 8) = stg[i]; } } while (0)
; __device__ __forceinline__ void xattn_phase(KA a, LAS unsigned char* lds, int G, const int tid, const int bid) {
;     ...
;         for (int kt = 0; kt < 4; ++kt) {
;             BAR_LDS();
;             XA_PUT_K();
;             XA_FETCH(u, kt + 1);
;             BAR_LDS();
; #pragma unroll
;             for (int n = 0; n < 4; ++n)
; #pragma unroll
;                 for (int ks = 0; ks < 8; ++ks) { const bf16x8 kf = *(const LAS bf16x8*)(Ks + (16 * n + fr) * KS + 32 * ks + 8 * fq); accS[kt * 4 + n] = __builtin_amdgcn_mfma_f32_16x16x32_bf16(kf, qf[ks], accS[kt * 4 + n], 0, 0, 0); }
;         }
	s_or_b32 s11, s10, 0x80
	v_add_u32_e32 v115, s20, v138
	s_movk_i32 s24, 0x3000
	v_add_u32_e32 v122, s20, v137
	v_add_u32_e32 v124, s20, v136
	v_add_u32_e32 v126, s20, v135
	v_add_u32_e32 v193, 0x8000, v140
	v_add_u32_e32 v194, 0x8000, v141
	v_add_u32_e32 v195, 0x8000, v142
	v_add_u32_e32 v196, 0xa000, v139
	v_add_u32_e32 v197, 0xa800, v139
	v_add_u32_e32 v198, 0xb000, v139
	v_add_u32_e32 v199, 0xb800, v139
	v_add_u32_e32 v200, 0xc800, v139
	v_add_u32_e32 v201, 0xd000, v139
	v_add_u32_e32 v202, 0xd800, v139
	v_add_u32_e32 v203, 0xe000, v139
	v_add_u32_e32 v204, 0xe800, v139
	v_add_u32_e32 v205, 0xf000, v139
	v_add_u32_e32 v206, 0xf800, v139
	s_waitcnt vmcnt(11)
	ds_read_b128 v[248:251], v149
	ds_read_b128 v[208:211], v149 offset:64
	ds_read_b128 v[212:215], v149 offset:128
	ds_read_b128 v[216:219], v149 offset:192
	ds_read_b128 v[220:223], v149 offset:256
	ds_read_b128 v[224:227], v149 offset:320
	ds_read_b128 v[228:231], v149 offset:384
	s_waitcnt lgkmcnt(6)
	v_mfma_f32_16x16x32_bf16 v[8:11], v[248:251], v[48:51], 0
	s_waitcnt vmcnt(10)
	ds_read_b128 v[232:235], v149 offset:448
	s_waitcnt lgkmcnt(6)
	v_mfma_f32_16x16x32_bf16 v[8:11], v[208:211], v[44:47], v[8:11]
	s_waitcnt vmcnt(9)
	ds_read_b128 v[236:239], v149 offset:8448
	s_waitcnt lgkmcnt(6)
	v_mfma_f32_16x16x32_bf16 v[8:11], v[212:215], v[40:43], v[8:11]
	s_waitcnt vmcnt(8)
	ds_read_b128 v[240:243], v149 offset:8512
	s_waitcnt lgkmcnt(6)
	v_mfma_f32_16x16x32_bf16 v[8:11], v[216:219], v[36:39], v[8:11]
	s_waitcnt vmcnt(7)
	ds_read_b128 v[244:247], v149 offset:8576
	s_waitcnt lgkmcnt(6)
	v_mfma_f32_16x16x32_bf16 v[8:11], v[220:223], v[32:35], v[8:11]
	s_waitcnt vmcnt(6)
	ds_read_b128 v[248:251], v149 offset:8640
	s_waitcnt lgkmcnt(6)
	v_mfma_f32_16x16x32_bf16 v[8:11], v[224:227], v[28:31], v[8:11]
	s_waitcnt vmcnt(5)
	ds_read_b128 v[208:211], v149 offset:8704
	s_waitcnt lgkmcnt(6)
	v_mfma_f32_16x16x32_bf16 v[8:11], v[228:231], v[4:7], v[8:11]
	s_waitcnt vmcnt(4)
	ds_read_b128 v[212:215], v149 offset:8768
	s_waitcnt lgkmcnt(6)
	v_mfma_f32_16x16x32_bf16 v[8:11], v[232:235], v[0:3], v[8:11]
	ds_read_b128 v[216:219], v149 offset:8832
	s_waitcnt lgkmcnt(6)
	v_mfma_f32_16x16x32_bf16 v[12:15], v[236:239], v[48:51], 0
	ds_read_b128 v[220:223], v149 offset:8896
	s_waitcnt lgkmcnt(6)
	v_mfma_f32_16x16x32_bf16 v[12:15], v[240:243], v[44:47], v[12:15]
	ds_read_b128 v[224:227], v149 offset:16896
	s_waitcnt lgkmcnt(6)
	v_mfma_f32_16x16x32_bf16 v[12:15], v[244:247], v[40:43], v[12:15]
	ds_read_b128 v[228:231], v149 offset:16960
	s_waitcnt lgkmcnt(6)
	v_mfma_f32_16x16x32_bf16 v[12:15], v[248:251], v[36:39], v[12:15]
	ds_read_b128 v[232:235], v149 offset:17024
	s_waitcnt lgkmcnt(6)
	v_mfma_f32_16x16x32_bf16 v[12:15], v[208:211], v[32:35], v[12:15]
	ds_read_b128 v[236:239], v149 offset:17088
	s_waitcnt lgkmcnt(6)
	v_mfma_f32_16x16x32_bf16 v[12:15], v[212:215], v[28:31], v[12:15]
	ds_read_b128 v[240:243], v149 offset:17152
	s_waitcnt lgkmcnt(6)
	v_mfma_f32_16x16x32_bf16 v[12:15], v[216:219], v[4:7], v[12:15]
	ds_read_b128 v[244:247], v149 offset:17216
	s_waitcnt lgkmcnt(6)
	v_mfma_f32_16x16x32_bf16 v[12:15], v[220:223], v[0:3], v[12:15]
	ds_read_b128 v[248:251], v149 offset:17280
	s_waitcnt lgkmcnt(6)
	v_mfma_f32_16x16x32_bf16 v[20:23], v[224:227], v[48:51], 0
	ds_read_b128 v[208:211], v149 offset:17344
	s_waitcnt lgkmcnt(6)
	v_mfma_f32_16x16x32_bf16 v[20:23], v[228:231], v[44:47], v[20:23]
	ds_read_b128 v[212:215], v149 offset:25344
	s_waitcnt lgkmcnt(6)
	v_mfma_f32_16x16x32_bf16 v[20:23], v[232:235], v[40:43], v[20:23]
	ds_read_b128 v[216:219], v149 offset:25408
	s_waitcnt lgkmcnt(6)
	v_mfma_f32_16x16x32_bf16 v[20:23], v[236:239], v[36:39], v[20:23]
	ds_read_b128 v[220:223], v149 offset:25472
	s_waitcnt lgkmcnt(6)
	v_mfma_f32_16x16x32_bf16 v[20:23], v[240:243], v[32:35], v[20:23]
	ds_read_b128 v[224:227], v149 offset:25536
	s_waitcnt lgkmcnt(6)
	v_mfma_f32_16x16x32_bf16 v[20:23], v[244:247], v[28:31], v[20:23]
	ds_read_b128 v[228:231], v149 offset:25600
	s_waitcnt lgkmcnt(6)
	v_mfma_f32_16x16x32_bf16 v[20:23], v[248:251], v[4:7], v[20:23]
	ds_read_b128 v[232:235], v149 offset:25664
	s_waitcnt lgkmcnt(6)
	v_mfma_f32_16x16x32_bf16 v[20:23], v[208:211], v[0:3], v[20:23]
	ds_read_b128 v[236:239], v149 offset:25728
	s_waitcnt lgkmcnt(6)
	v_mfma_f32_16x16x32_bf16 v[64:67], v[212:215], v[48:51], 0
	s_waitcnt lgkmcnt(5)
	v_mfma_f32_16x16x32_bf16 v[64:67], v[216:219], v[44:47], v[64:67]
	s_waitcnt lgkmcnt(4)
	v_mfma_f32_16x16x32_bf16 v[64:67], v[220:223], v[40:43], v[64:67]
	s_waitcnt lgkmcnt(3)
	v_mfma_f32_16x16x32_bf16 v[64:67], v[224:227], v[36:39], v[64:67]
	s_waitcnt lgkmcnt(2)
	v_mfma_f32_16x16x32_bf16 v[64:67], v[228:231], v[32:35], v[64:67]
	s_waitcnt lgkmcnt(1)
	v_mfma_f32_16x16x32_bf16 v[64:67], v[232:235], v[28:31], v[64:67]
	s_waitcnt lgkmcnt(0)
	v_mfma_f32_16x16x32_bf16 v[64:67], v[236:239], v[4:7], v[64:67]
	ds_read_b128 v[240:243], v149 offset:25792
	s_waitcnt lgkmcnt(0)
	s_barrier
	s_waitcnt vmcnt(0)
	ds_write_b128 v145, v[60:63]
	ds_write_b128 v146, v[56:59]
	ds_write_b128 v147, v[52:55]
	ds_write_b128 v148, v[24:27]
	v_add_u32_e32 v24, s11, v128
	v_add_u32_e32 v52, s11, v129
	v_add_u32_e32 v56, s11, v130
	v_add_u32_e32 v60, s11, v131
	v_ashrrev_i32_e32 v25, 31, v24
	v_ashrrev_i32_e32 v53, 31, v52
	v_ashrrev_i32_e32 v57, 31, v56
	v_ashrrev_i32_e32 v61, 31, v60
	v_lshlrev_b64 v[24:25], 11, v[24:25]
	v_lshlrev_b64 v[52:53], 11, v[52:53]
	v_lshlrev_b64 v[56:57], 11, v[56:57]
	v_lshlrev_b64 v[60:61], 11, v[60:61]
	v_lshl_add_u64 v[24:25], v[84:85], 0, v[24:25]
	v_lshl_add_u64 v[52:53], v[84:85], 0, v[52:53]
	v_lshl_add_u64 v[56:57], v[84:85], 0, v[56:57]
	v_lshl_add_u64 v[60:61], v[84:85], 0, v[60:61]
	global_load_dwordx4 v[24:27], v[24:25], off
	s_waitcnt lgkmcnt(4)
	v_mfma_f32_16x16x32_bf16 v[64:67], v[240:243], v[0:3], v[64:67]
	global_load_dwordx4 v[52:55], v[52:53], off
	s_or_b32 s11, s10, 0xc0
	global_load_dwordx4 v[56:59], v[56:57], off
	s_nop 0
	global_load_dwordx4 v[60:63], v[60:61], off
	s_waitcnt lgkmcnt(0)
	s_barrier
; #define LAS __attribute__((address_space(3)))
; #define BAR_LDS() do { asm volatile("s_waitcnt lgkmcnt(0)" ::: "memory"); __builtin_amdgcn_s_barrier(); asm volatile("" ::: "memory"); } while (0)
; #define XA_PUT_K() do { _Pragma("unroll") for (int i = 0; i < 4; ++i) { const int cidx = tid + 512 * i, r = cidx >> 5, c8 = cidx & 31; *(LAS u32x4*)(Ks + r * KS + c8 * 8) = stg[i]; } } while (0)
; __device__ __forceinline__ void xattn_phase(KA a, LAS unsigned char* lds, int G, const int tid, const int bid) {
;     ...
;         for (int kt = 0; kt < 4; ++kt) {
;             BAR_LDS();
;             XA_PUT_K();
;             XA_FETCH(u, kt + 1);
;             BAR_LDS();
; #pragma unroll
;             for (int n = 0; n < 4; ++n)
; #pragma unroll
;                 for (int ks = 0; ks < 8; ++ks) { const bf16x8 kf = *(const LAS bf16x8*)(Ks + (16 * n + fr) * KS + 32 * ks + 8 * fq); accS[kt * 4 + n] = __builtin_amdgcn_mfma_f32_16x16x32_bf16(kf, qf[ks], accS[kt * 4 + n], 0, 0, 0); }
;         }
	ds_read_b128 v[208:211], v149
	ds_read_b128 v[212:215], v149 offset:64
	ds_read_b128 v[216:219], v149 offset:128
	ds_read_b128 v[220:223], v149 offset:192
	ds_read_b128 v[224:227], v149 offset:256
	ds_read_b128 v[228:231], v149 offset:320
	ds_read_b128 v[232:235], v149 offset:384
	s_waitcnt lgkmcnt(6)
	v_mfma_f32_16x16x32_bf16 v[68:71], v[208:211], v[48:51], 0
	ds_read_b128 v[236:239], v149 offset:448
	s_waitcnt lgkmcnt(6)
	v_mfma_f32_16x16x32_bf16 v[68:71], v[212:215], v[44:47], v[68:71]
	ds_read_b128 v[240:243], v149 offset:8448
	s_waitcnt lgkmcnt(6)
	v_mfma_f32_16x16x32_bf16 v[68:71], v[216:219], v[40:43], v[68:71]
	ds_read_b128 v[244:247], v149 offset:8512
	s_waitcnt lgkmcnt(6)
	v_mfma_f32_16x16x32_bf16 v[68:71], v[220:223], v[36:39], v[68:71]
	ds_read_b128 v[248:251], v149 offset:8576
	s_waitcnt lgkmcnt(6)
	v_mfma_f32_16x16x32_bf16 v[68:71], v[224:227], v[32:35], v[68:71]
	ds_read_b128 v[208:211], v149 offset:8640
	s_waitcnt lgkmcnt(6)
	v_mfma_f32_16x16x32_bf16 v[68:71], v[228:231], v[28:31], v[68:71]
	ds_read_b128 v[212:215], v149 offset:8704
	s_waitcnt lgkmcnt(6)
	v_mfma_f32_16x16x32_bf16 v[68:71], v[232:235], v[4:7], v[68:71]
	ds_read_b128 v[216:219], v149 offset:8768
	s_waitcnt lgkmcnt(6)
	v_mfma_f32_16x16x32_bf16 v[68:71], v[236:239], v[0:3], v[68:71]
	ds_read_b128 v[220:223], v149 offset:8832
	s_waitcnt lgkmcnt(6)
	v_mfma_f32_16x16x32_bf16 v[72:75], v[240:243], v[48:51], 0
	ds_read_b128 v[224:227], v149 offset:8896
	s_waitcnt lgkmcnt(6)
	v_mfma_f32_16x16x32_bf16 v[72:75], v[244:247], v[44:47], v[72:75]
	ds_read_b128 v[228:231], v149 offset:16896
	s_waitcnt lgkmcnt(6)
	v_mfma_f32_16x16x32_bf16 v[72:75], v[248:251], v[40:43], v[72:75]
	ds_read_b128 v[232:235], v149 offset:16960
	s_waitcnt lgkmcnt(6)
	v_mfma_f32_16x16x32_bf16 v[72:75], v[208:211], v[36:39], v[72:75]
	ds_read_b128 v[236:239], v149 offset:17024
	s_waitcnt lgkmcnt(6)
	v_mfma_f32_16x16x32_bf16 v[72:75], v[212:215], v[32:35], v[72:75]
	ds_read_b128 v[240:243], v149 offset:17088
	s_waitcnt lgkmcnt(6)
	v_mfma_f32_16x16x32_bf16 v[72:75], v[216:219], v[28:31], v[72:75]
	ds_read_b128 v[244:247], v149 offset:17152
	s_waitcnt lgkmcnt(6)
	v_mfma_f32_16x16x32_bf16 v[72:75], v[220:223], v[4:7], v[72:75]
	ds_read_b128 v[248:251], v149 offset:17216
	s_waitcnt lgkmcnt(6)
	v_mfma_f32_16x16x32_bf16 v[72:75], v[224:227], v[0:3], v[72:75]
	ds_read_b128 v[208:211], v149 offset:17280
	s_waitcnt lgkmcnt(6)
	v_mfma_f32_16x16x32_bf16 v[76:79], v[228:231], v[48:51], 0
	ds_read_b128 v[212:215], v149 offset:17344
	s_waitcnt lgkmcnt(6)
	v_mfma_f32_16x16x32_bf16 v[76:79], v[232:235], v[44:47], v[76:79]
	ds_read_b128 v[216:219], v149 offset:25344
	s_waitcnt lgkmcnt(6)
	v_mfma_f32_16x16x32_bf16 v[76:79], v[236:239], v[40:43], v[76:79]
	ds_read_b128 v[220:223], v149 offset:25408
	s_waitcnt lgkmcnt(6)
	v_mfma_f32_16x16x32_bf16 v[76:79], v[240:243], v[36:39], v[76:79]
	ds_read_b128 v[224:227], v149 offset:25472
	s_waitcnt lgkmcnt(6)
	v_mfma_f32_16x16x32_bf16 v[76:79], v[244:247], v[32:35], v[76:79]
	ds_read_b128 v[228:231], v149 offset:25536
	s_waitcnt lgkmcnt(6)
	v_mfma_f32_16x16x32_bf16 v[76:79], v[248:251], v[28:31], v[76:79]
	ds_read_b128 v[232:235], v149 offset:25600
	s_waitcnt lgkmcnt(6)
	v_mfma_f32_16x16x32_bf16 v[76:79], v[208:211], v[4:7], v[76:79]
	ds_read_b128 v[236:239], v149 offset:25664
	s_waitcnt lgkmcnt(6)
	v_mfma_f32_16x16x32_bf16 v[76:79], v[212:215], v[0:3], v[76:79]
	ds_read_b128 v[240:243], v149 offset:25728
	s_waitcnt lgkmcnt(6)
	v_mfma_f32_16x16x32_bf16 v[80:83], v[216:219], v[48:51], 0
	s_waitcnt lgkmcnt(5)
	v_mfma_f32_16x16x32_bf16 v[80:83], v[220:223], v[44:47], v[80:83]
	s_waitcnt lgkmcnt(4)
	v_mfma_f32_16x16x32_bf16 v[80:83], v[224:227], v[40:43], v[80:83]
	s_waitcnt lgkmcnt(3)
	v_mfma_f32_16x16x32_bf16 v[80:83], v[228:231], v[36:39], v[80:83]
	s_waitcnt lgkmcnt(2)
	v_mfma_f32_16x16x32_bf16 v[80:83], v[232:235], v[32:35], v[80:83]
	s_waitcnt lgkmcnt(1)
	v_mfma_f32_16x16x32_bf16 v[80:83], v[236:239], v[28:31], v[80:83]
	s_waitcnt lgkmcnt(0)
	v_mfma_f32_16x16x32_bf16 v[80:83], v[240:243], v[4:7], v[80:83]
	ds_read_b128 v[244:247], v149 offset:25792
	s_waitcnt lgkmcnt(0)
	s_barrier
	s_waitcnt vmcnt(0)
	ds_write_b128 v145, v[60:63]
	ds_write_b128 v146, v[56:59]
	ds_write_b128 v147, v[52:55]
	ds_write_b128 v148, v[24:27]
	v_add_u32_e32 v24, s11, v128
	v_add_u32_e32 v52, s11, v129
	v_add_u32_e32 v56, s11, v130
	v_add_u32_e32 v60, s11, v131
	v_ashrrev_i32_e32 v25, 31, v24
	v_ashrrev_i32_e32 v53, 31, v52
	v_ashrrev_i32_e32 v57, 31, v56
	v_ashrrev_i32_e32 v61, 31, v60
	v_lshlrev_b64 v[24:25], 11, v[24:25]
	v_lshlrev_b64 v[52:53], 11, v[52:53]
	v_lshlrev_b64 v[56:57], 11, v[56:57]
	v_lshlrev_b64 v[60:61], 11, v[60:61]
	v_lshl_add_u64 v[24:25], v[84:85], 0, v[24:25]
	v_lshl_add_u64 v[52:53], v[84:85], 0, v[52:53]
	v_lshl_add_u64 v[56:57], v[84:85], 0, v[56:57]
	v_lshl_add_u64 v[60:61], v[84:85], 0, v[60:61]
	global_load_dwordx4 v[24:27], v[24:25], off
	s_waitcnt lgkmcnt(4)
	v_mfma_f32_16x16x32_bf16 v[80:83], v[244:247], v[0:3], v[80:83]
	global_load_dwordx4 v[52:55], v[52:53], off
	s_ashr_i32 s11, s10, 31
	global_load_dwordx4 v[56:59], v[56:57], off
	s_lshl_b64 s[10:11], s[10:11], 1
	global_load_dwordx4 v[60:63], v[60:61], off
	s_waitcnt lgkmcnt(0)
	s_barrier
; #define LAS __attribute__((address_space(3)))
; #define BAR_LDS() do { asm volatile("s_waitcnt lgkmcnt(0)" ::: "memory"); __builtin_amdgcn_s_barrier(); asm volatile("" ::: "memory"); } while (0)
; #define XA_PUT_K() do { _Pragma("unroll") for (int i = 0; i < 4; ++i) { const int cidx = tid + 512 * i, r = cidx >> 5, c8 = cidx & 31; *(LAS u32x4*)(Ks + r * KS + c8 * 8) = stg[i]; } } while (0)
; __device__ __forceinline__ void xattn_phase(KA a, LAS unsigned char* lds, int G, const int tid, const int bid) {
;     ...
;         for (int kt = 0; kt < 4; ++kt) {
;             BAR_LDS();
;             XA_PUT_K();
;             XA_FETCH(u, kt + 1);
;             BAR_LDS();
; #pragma unroll
;             for (int n = 0; n < 4; ++n)
; #pragma unroll
;                 for (int ks = 0; ks < 8; ++ks) { const bf16x8 kf = *(const LAS bf16x8*)(Ks + (16 * n + fr) * KS + 32 * ks + 8 * fq); accS[kt * 4 + n] = __builtin_amdgcn_mfma_f32_16x16x32_bf16(kf, qf[ks], accS[kt * 4 + n], 0, 0, 0); }
;         }
	ds_read_b128 v[248:251], v149
	ds_read_b128 v[208:211], v149 offset:64
	ds_read_b128 v[212:215], v149 offset:128
	ds_read_b128 v[216:219], v149 offset:192
	ds_read_b128 v[220:223], v149 offset:256
	ds_read_b128 v[224:227], v149 offset:320
	ds_read_b128 v[228:231], v149 offset:384
	s_waitcnt lgkmcnt(6)
	v_mfma_f32_16x16x32_bf16 v[84:87], v[248:251], v[48:51], 0
	ds_read_b128 v[232:235], v149 offset:448
	s_waitcnt lgkmcnt(6)
	v_mfma_f32_16x16x32_bf16 v[84:87], v[208:211], v[44:47], v[84:87]
	ds_read_b128 v[236:239], v149 offset:8448
	s_waitcnt lgkmcnt(6)
	v_mfma_f32_16x16x32_bf16 v[84:87], v[212:215], v[40:43], v[84:87]
	ds_read_b128 v[240:243], v149 offset:8512
	s_waitcnt lgkmcnt(6)
	v_mfma_f32_16x16x32_bf16 v[84:87], v[216:219], v[36:39], v[84:87]
	ds_read_b128 v[244:247], v149 offset:8576
	s_waitcnt lgkmcnt(6)
	v_mfma_f32_16x16x32_bf16 v[84:87], v[220:223], v[32:35], v[84:87]
	ds_read_b128 v[248:251], v149 offset:8640
	s_waitcnt lgkmcnt(6)
	v_mfma_f32_16x16x32_bf16 v[84:87], v[224:227], v[28:31], v[84:87]
	ds_read_b128 v[208:211], v149 offset:8704
	s_waitcnt lgkmcnt(6)
	v_mfma_f32_16x16x32_bf16 v[84:87], v[228:231], v[4:7], v[84:87]
	ds_read_b128 v[212:215], v149 offset:8768
	s_waitcnt lgkmcnt(6)
	v_mfma_f32_16x16x32_bf16 v[84:87], v[232:235], v[0:3], v[84:87]
	ds_read_b128 v[216:219], v149 offset:8832
	s_waitcnt lgkmcnt(6)
	v_mfma_f32_16x16x32_bf16 v[88:91], v[236:239], v[48:51], 0
	ds_read_b128 v[220:223], v149 offset:8896
	s_waitcnt lgkmcnt(6)
	v_mfma_f32_16x16x32_bf16 v[88:91], v[240:243], v[44:47], v[88:91]
	ds_read_b128 v[224:227], v149 offset:16896
	s_waitcnt lgkmcnt(6)
	v_mfma_f32_16x16x32_bf16 v[88:91], v[244:247], v[40:43], v[88:91]
	ds_read_b128 v[228:231], v149 offset:16960
	s_waitcnt lgkmcnt(6)
	v_mfma_f32_16x16x32_bf16 v[88:91], v[248:251], v[36:39], v[88:91]
	ds_read_b128 v[232:235], v149 offset:17024
	s_waitcnt lgkmcnt(6)
	v_mfma_f32_16x16x32_bf16 v[88:91], v[208:211], v[32:35], v[88:91]
	ds_read_b128 v[236:239], v149 offset:17088
	s_waitcnt lgkmcnt(6)
	v_mfma_f32_16x16x32_bf16 v[88:91], v[212:215], v[28:31], v[88:91]
	ds_read_b128 v[240:243], v149 offset:17152
	s_waitcnt lgkmcnt(6)
	v_mfma_f32_16x16x32_bf16 v[88:91], v[216:219], v[4:7], v[88:91]
	ds_read_b128 v[244:247], v149 offset:17216
	s_waitcnt lgkmcnt(6)
	v_mfma_f32_16x16x32_bf16 v[88:91], v[220:223], v[0:3], v[88:91]
	ds_read_b128 v[248:251], v149 offset:17280
	s_waitcnt lgkmcnt(6)
	v_mfma_f32_16x16x32_bf16 v[92:95], v[224:227], v[48:51], 0
	ds_read_b128 v[208:211], v149 offset:17344
	s_waitcnt lgkmcnt(6)
	v_mfma_f32_16x16x32_bf16 v[92:95], v[228:231], v[44:47], v[92:95]
	ds_read_b128 v[212:215], v149 offset:25344
	s_waitcnt lgkmcnt(6)
	v_mfma_f32_16x16x32_bf16 v[92:95], v[232:235], v[40:43], v[92:95]
	ds_read_b128 v[216:219], v149 offset:25408
	s_waitcnt lgkmcnt(6)
	v_mfma_f32_16x16x32_bf16 v[92:95], v[236:239], v[36:39], v[92:95]
	ds_read_b128 v[220:223], v149 offset:25472
	s_waitcnt lgkmcnt(6)
	v_mfma_f32_16x16x32_bf16 v[92:95], v[240:243], v[32:35], v[92:95]
	ds_read_b128 v[224:227], v149 offset:25536
	s_waitcnt lgkmcnt(6)
	v_mfma_f32_16x16x32_bf16 v[92:95], v[244:247], v[28:31], v[92:95]
	ds_read_b128 v[228:231], v149 offset:25600
	s_waitcnt lgkmcnt(6)
	v_mfma_f32_16x16x32_bf16 v[92:95], v[248:251], v[4:7], v[92:95]
	ds_read_b128 v[232:235], v149 offset:25664
	s_waitcnt lgkmcnt(6)
	v_mfma_f32_16x16x32_bf16 v[92:95], v[208:211], v[0:3], v[92:95]
	ds_read_b128 v[236:239], v149 offset:25728
	s_waitcnt lgkmcnt(6)
	v_mfma_f32_16x16x32_bf16 v[96:99], v[212:215], v[48:51], 0
	s_waitcnt lgkmcnt(5)
	v_mfma_f32_16x16x32_bf16 v[96:99], v[216:219], v[44:47], v[96:99]
	s_waitcnt lgkmcnt(4)
	v_mfma_f32_16x16x32_bf16 v[96:99], v[220:223], v[40:43], v[96:99]
	s_waitcnt lgkmcnt(3)
	v_mfma_f32_16x16x32_bf16 v[96:99], v[224:227], v[36:39], v[96:99]
	s_waitcnt lgkmcnt(2)
	v_mfma_f32_16x16x32_bf16 v[96:99], v[228:231], v[32:35], v[96:99]
	s_waitcnt lgkmcnt(1)
	v_mfma_f32_16x16x32_bf16 v[96:99], v[232:235], v[28:31], v[96:99]
	s_waitcnt lgkmcnt(0)
	v_mfma_f32_16x16x32_bf16 v[96:99], v[236:239], v[4:7], v[96:99]
	ds_read_b128 v[240:243], v149 offset:25792
	s_waitcnt lgkmcnt(0)
	s_barrier
	s_waitcnt vmcnt(0)
	ds_write_b128 v145, v[60:63]
	ds_write_b128 v146, v[56:59]
	ds_write_b128 v147, v[52:55]
	ds_write_b128 v148, v[24:27]
	v_lshl_add_u64 v[60:61], v[112:113], 0, s[10:11]
	v_mad_i64_i32 v[24:25], s[22:23], v115, s24, v[60:61]
	v_mad_i64_i32 v[52:53], s[22:23], v122, s24, v[60:61]
	v_mad_i64_i32 v[56:57], s[22:23], v124, s24, v[60:61]
	v_mad_i64_i32 v[60:61], s[20:21], v126, s24, v[60:61]
	global_load_dwordx4 v[24:27], v[24:25], off
	s_waitcnt lgkmcnt(4)
	v_mfma_f32_16x16x32_bf16 v[96:99], v[240:243], v[0:3], v[96:99]
	global_load_dwordx4 v[52:55], v[52:53], off
	s_mov_b32 s20, 0xff61b1e6
	global_load_dwordx4 v[56:59], v[56:57], off
	s_add_u32 s10, s6, s10
	global_load_dwordx4 v[60:63], v[60:61], off
	s_waitcnt lgkmcnt(0)
	s_barrier
; #define LAS __attribute__((address_space(3)))
; #define BAR_LDS() do { asm volatile("s_waitcnt lgkmcnt(0)" ::: "memory"); __builtin_amdgcn_s_barrier(); asm volatile("" ::: "memory"); } while (0)
; #define XA_PUT_K() do { _Pragma("unroll") for (int i = 0; i < 4; ++i) { const int cidx = tid + 512 * i, r = cidx >> 5, c8 = cidx & 31; *(LAS u32x4*)(Ks + r * KS + c8 * 8) = stg[i]; } } while (0)
; __device__ __forceinline__ void xattn_phase(KA a, LAS unsigned char* lds, int G, const int tid, const int bid) {
;     ...
;         for (int kt = 0; kt < 4; ++kt) {
;             BAR_LDS();
;             XA_PUT_K();
;             XA_FETCH(u, kt + 1);
;             BAR_LDS();
; #pragma unroll
;             for (int n = 0; n < 4; ++n)
; #pragma unroll
;                 for (int ks = 0; ks < 8; ++ks) { const bf16x8 kf = *(const LAS bf16x8*)(Ks + (16 * n + fr) * KS + 32 * ks + 8 * fq); accS[kt * 4 + n] = __builtin_amdgcn_mfma_f32_16x16x32_bf16(kf, qf[ks], accS[kt * 4 + n], 0, 0, 0); }
;         }
	ds_read_b128 v[244:247], v149
	ds_read_b128 v[248:251], v149 offset:64
	ds_read_b128 v[208:211], v149 offset:128
	ds_read_b128 v[212:215], v149 offset:192
	ds_read_b128 v[216:219], v149 offset:256
	ds_read_b128 v[220:223], v149 offset:320
	ds_read_b128 v[224:227], v149 offset:384
	s_waitcnt lgkmcnt(6)
	v_mfma_f32_16x16x32_bf16 v[100:103], v[244:247], v[48:51], 0
	s_addc_u32 s11, s7, s11
	ds_read_b128 v[228:231], v149 offset:448
	s_waitcnt lgkmcnt(6)
	v_mfma_f32_16x16x32_bf16 v[100:103], v[248:251], v[44:47], v[100:103]
	s_cmpk_lt_i32 s16, 0xa00
	ds_read_b128 v[232:235], v149 offset:8448
	s_waitcnt lgkmcnt(6)
	v_mfma_f32_16x16x32_bf16 v[100:103], v[208:211], v[40:43], v[100:103]
	ds_read_b128 v[236:239], v149 offset:8512
	s_waitcnt lgkmcnt(6)
	v_mfma_f32_16x16x32_bf16 v[100:103], v[212:215], v[36:39], v[100:103]
	ds_read_b128 v[240:243], v149 offset:8576
	s_waitcnt lgkmcnt(6)
	v_mfma_f32_16x16x32_bf16 v[100:103], v[216:219], v[32:35], v[100:103]
	ds_read_b128 v[244:247], v149 offset:8640
	s_waitcnt lgkmcnt(6)
	v_mfma_f32_16x16x32_bf16 v[100:103], v[220:223], v[28:31], v[100:103]
	ds_read_b128 v[248:251], v149 offset:8704
	s_waitcnt lgkmcnt(6)
	v_mfma_f32_16x16x32_bf16 v[100:103], v[224:227], v[4:7], v[100:103]
	ds_read_b128 v[208:211], v149 offset:8768
	s_waitcnt lgkmcnt(6)
	v_mfma_f32_16x16x32_bf16 v[100:103], v[228:231], v[0:3], v[100:103]
	ds_read_b128 v[212:215], v149 offset:8832
	s_waitcnt lgkmcnt(6)
	v_mfma_f32_16x16x32_bf16 v[104:107], v[232:235], v[48:51], 0
	ds_read_b128 v[216:219], v149 offset:8896
	s_waitcnt lgkmcnt(6)
	v_mfma_f32_16x16x32_bf16 v[104:107], v[236:239], v[44:47], v[104:107]
	ds_read_b128 v[220:223], v149 offset:16896
	s_waitcnt lgkmcnt(6)
	v_mfma_f32_16x16x32_bf16 v[104:107], v[240:243], v[40:43], v[104:107]
	ds_read_b128 v[224:227], v149 offset:16960
	s_waitcnt lgkmcnt(6)
	v_mfma_f32_16x16x32_bf16 v[104:107], v[244:247], v[36:39], v[104:107]
	ds_read_b128 v[228:231], v149 offset:17024
	s_waitcnt lgkmcnt(6)
	v_mfma_f32_16x16x32_bf16 v[104:107], v[248:251], v[32:35], v[104:107]
	ds_read_b128 v[232:235], v149 offset:17088
	s_waitcnt lgkmcnt(6)
	v_mfma_f32_16x16x32_bf16 v[104:107], v[208:211], v[28:31], v[104:107]
	ds_read_b128 v[236:239], v149 offset:17152
	s_waitcnt lgkmcnt(6)
	v_mfma_f32_16x16x32_bf16 v[104:107], v[212:215], v[4:7], v[104:107]
	ds_read_b128 v[240:243], v149 offset:17216
	s_waitcnt lgkmcnt(6)
	v_mfma_f32_16x16x32_bf16 v[104:107], v[216:219], v[0:3], v[104:107]
	ds_read_b128 v[244:247], v149 offset:17280
	s_waitcnt lgkmcnt(6)
	v_mfma_f32_16x16x32_bf16 v[108:111], v[220:223], v[48:51], 0
	ds_read_b128 v[248:251], v149 offset:17344
	s_waitcnt lgkmcnt(6)
	v_mfma_f32_16x16x32_bf16 v[108:111], v[224:227], v[44:47], v[108:111]
	ds_read_b128 v[208:211], v149 offset:25344
	s_waitcnt lgkmcnt(6)
	v_mfma_f32_16x16x32_bf16 v[108:111], v[228:231], v[40:43], v[108:111]
	ds_read_b128 v[212:215], v149 offset:25408
	s_waitcnt lgkmcnt(6)
	v_mfma_f32_16x16x32_bf16 v[108:111], v[232:235], v[36:39], v[108:111]
	ds_read_b128 v[216:219], v149 offset:25472
	s_waitcnt lgkmcnt(6)
	v_mfma_f32_16x16x32_bf16 v[108:111], v[236:239], v[32:35], v[108:111]
	ds_read_b128 v[220:223], v149 offset:25536
	s_waitcnt lgkmcnt(6)
	v_mfma_f32_16x16x32_bf16 v[108:111], v[240:243], v[28:31], v[108:111]
	ds_read_b128 v[224:227], v149 offset:25600
	s_waitcnt lgkmcnt(6)
	v_mfma_f32_16x16x32_bf16 v[108:111], v[244:247], v[4:7], v[108:111]
	ds_read_b128 v[228:231], v149 offset:25664
	s_waitcnt lgkmcnt(6)
	v_mfma_f32_16x16x32_bf16 v[108:111], v[248:251], v[0:3], v[108:111]
	ds_read_b128 v[232:235], v149 offset:25728
	s_waitcnt lgkmcnt(6)
	v_mfma_f32_16x16x32_bf16 v[48:51], v[208:211], v[48:51], 0
	s_waitcnt lgkmcnt(5)
	v_mfma_f32_16x16x32_bf16 v[44:47], v[212:215], v[44:47], v[48:51]
	s_nop 4
	s_waitcnt lgkmcnt(4)
	v_mfma_f32_16x16x32_bf16 v[40:43], v[216:219], v[40:43], v[44:47]
	s_nop 2
	s_waitcnt lgkmcnt(3)
	v_mfma_f32_16x16x32_bf16 v[36:39], v[220:223], v[36:39], v[40:43]
	s_nop 2
	s_waitcnt lgkmcnt(2)
	v_mfma_f32_16x16x32_bf16 v[32:35], v[224:227], v[32:35], v[36:39]
	s_nop 2
	s_waitcnt lgkmcnt(1)
	v_mfma_f32_16x16x32_bf16 v[28:31], v[228:231], v[28:31], v[32:35]
	s_nop 2
	s_waitcnt lgkmcnt(0)
	v_mfma_f32_16x16x32_bf16 v[4:7], v[232:235], v[4:7], v[28:31]
	s_nop 2
	ds_read_b128 v[236:239], v149 offset:25792
	s_waitcnt lgkmcnt(0)
	s_barrier
; __device__ __forceinline__ void xattn_phase(KA a, LAS unsigned char* lds, int G, const int tid, const int bid) {
;     ...
;         float mx = -3.0e38f;
; #pragma unroll
;         for (int n = 0; n < 16; ++n)
; #pragma unroll
;             for (int i = 0; i < 4; ++i) mx = fmaxf(mx, accS[n][i]);
;         mx = fmaxf(mx, __shfl_xor(mx, 16)); mx = fmaxf(mx, __shfl_xor(mx, 32));
;         float sum = 0.f;
; #pragma unroll
;         for (int n = 0; n < 16; ++n)
; #pragma unroll
;             for (int i = 0; i < 4; ++i) { const float p = __builtin_amdgcn_exp2f(accS[n][i] - mx); accS[n][i] = p; sum += p; }
;         sum += __shfl_xor(sum, 16); sum += __shfl_xor(sum, 32);
	s_waitcnt lgkmcnt(0)
	v_mfma_f32_16x16x32_bf16 v[0:3], v[236:239], v[0:3], v[4:7]
	s_nop 2
	v_max3_f32 v4, v8, s20, v9
	v_max3_f32 v4, v4, v10, v11
	v_max3_f32 v4, v4, v12, v13
	v_max3_f32 v4, v4, v14, v15
	v_max3_f32 v4, v4, v20, v21
	v_max3_f32 v4, v4, v22, v23
	v_max3_f32 v4, v4, v64, v65
	v_max3_f32 v4, v4, v66, v67
	v_max3_f32 v4, v4, v68, v69
	v_max3_f32 v4, v4, v70, v71
	v_max3_f32 v4, v4, v72, v73
	v_max3_f32 v4, v4, v74, v75
	v_max3_f32 v4, v4, v76, v77
	v_max3_f32 v4, v4, v78, v79
	v_max3_f32 v4, v4, v80, v81
	v_max3_f32 v4, v4, v82, v83
	v_max3_f32 v4, v4, v84, v85
	v_max3_f32 v4, v4, v86, v87
	v_max3_f32 v4, v4, v88, v89
	v_max3_f32 v4, v4, v90, v91
	v_max3_f32 v4, v4, v92, v93
	v_max3_f32 v4, v4, v94, v95
	v_max3_f32 v4, v4, v96, v97
	v_max3_f32 v4, v4, v98, v99
	v_max3_f32 v4, v4, v100, v101
	v_max3_f32 v4, v4, v102, v103
	v_max3_f32 v4, v4, v104, v105
	v_max3_f32 v4, v4, v106, v107
	v_max3_f32 v4, v4, v108, v109
	v_xor_b32_e32 v5, 16, v164
	v_max3_f32 v4, v4, v110, v111
	v_cmp_lt_i32_e32 vcc, v5, v166
	v_max3_f32 v4, v4, v0, v1
	v_max3_f32 v4, v4, v2, v3
	v_cndmask_b32_e32 v5, v164, v5, vcc
	v_lshlrev_b32_e32 v5, 2, v5
	ds_bpermute_b32 v6, v5, v4
	s_waitcnt vmcnt(0)
	ds_write2_b64 v150, v[60:61], v[62:63] offset1:1
	ds_write2_b64 v151, v[56:57], v[58:59] offset1:1
	ds_write2_b64 v152, v[52:53], v[54:55] offset1:1
	ds_write2_b64 v153, v[24:25], v[26:27] offset1:1
	s_waitcnt lgkmcnt(4)
	v_max_f32_e32 v6, v6, v6
	v_max_f32_e32 v4, v4, v6
	v_xor_b32_e32 v6, 32, v164
	v_cmp_lt_i32_e32 vcc, v6, v166
	s_nop 1
	v_cndmask_b32_e32 v6, v164, v6, vcc
	v_lshlrev_b32_e32 v6, 2, v6
	ds_bpermute_b32 v7, v6, v4
	s_waitcnt lgkmcnt(0)
	v_max_f32_e32 v7, v7, v7
	v_max_f32_e32 v4, v4, v7
	v_sub_f32_e32 v7, v8, v4
	v_exp_f32_e32 v7, v7
	v_sub_f32_e32 v9, v9, v4
	v_exp_f32_e32 v9, v9
	v_sub_f32_e32 v10, v10, v4
	v_exp_f32_e32 v10, v10
	v_sub_f32_e32 v11, v11, v4
	v_exp_f32_e32 v11, v11
	v_sub_f32_e32 v12, v12, v4
	v_add_f32_e32 v8, 0, v7
	v_exp_f32_e32 v12, v12
	v_sub_f32_e32 v13, v13, v4
	v_add_f32_e32 v8, v9, v8
	v_exp_f32_e32 v13, v13
	v_sub_f32_e32 v14, v14, v4
	v_add_f32_e32 v8, v10, v8
	v_exp_f32_e32 v14, v14
	v_sub_f32_e32 v15, v15, v4
	v_add_f32_e32 v8, v11, v8
	v_exp_f32_e32 v15, v15
	v_sub_f32_e32 v20, v20, v4
	v_add_f32_e32 v8, v12, v8
	v_exp_f32_e32 v20, v20
	v_sub_f32_e32 v21, v21, v4
	v_add_f32_e32 v8, v13, v8
	v_exp_f32_e32 v21, v21
	v_sub_f32_e32 v22, v22, v4
	v_add_f32_e32 v8, v14, v8
	v_exp_f32_e32 v22, v22
	v_sub_f32_e32 v23, v23, v4
	v_add_f32_e32 v8, v15, v8
	v_exp_f32_e32 v23, v23
	v_sub_f32_e32 v28, v64, v4
	v_add_f32_e32 v8, v20, v8
	v_exp_f32_e32 v32, v28
	v_sub_f32_e32 v28, v65, v4
	v_add_f32_e32 v8, v21, v8
	v_exp_f32_e32 v33, v28
	v_sub_f32_e32 v28, v66, v4
	v_add_f32_e32 v8, v22, v8
	v_exp_f32_e32 v34, v28
	v_sub_f32_e32 v28, v67, v4
	v_add_f32_e32 v8, v23, v8
	v_exp_f32_e32 v35, v28
	v_sub_f32_e32 v28, v68, v4
	v_add_f32_e32 v8, v32, v8
	v_exp_f32_e32 v36, v28
	v_sub_f32_e32 v28, v69, v4
	v_add_f32_e32 v8, v33, v8
	v_exp_f32_e32 v37, v28
	v_sub_f32_e32 v28, v70, v4
	v_add_f32_e32 v8, v34, v8
	v_exp_f32_e32 v38, v28
	v_sub_f32_e32 v28, v71, v4
	v_add_f32_e32 v8, v35, v8
	v_exp_f32_e32 v39, v28
	v_sub_f32_e32 v28, v72, v4
	v_add_f32_e32 v8, v36, v8
	v_exp_f32_e32 v40, v28
	v_sub_f32_e32 v28, v73, v4
	v_add_f32_e32 v8, v37, v8
	v_exp_f32_e32 v41, v28
	v_sub_f32_e32 v28, v74, v4
	v_add_f32_e32 v8, v38, v8
	v_exp_f32_e32 v42, v28
	v_sub_f32_e32 v28, v75, v4
	v_add_f32_e32 v8, v39, v8
	v_exp_f32_e32 v43, v28
	v_sub_f32_e32 v28, v76, v4
	v_add_f32_e32 v8, v40, v8
	v_exp_f32_e32 v44, v28
	v_sub_f32_e32 v28, v77, v4
	v_add_f32_e32 v8, v41, v8
	v_exp_f32_e32 v45, v28
	v_sub_f32_e32 v28, v78, v4
	v_add_f32_e32 v8, v42, v8
	v_exp_f32_e32 v46, v28
	v_sub_f32_e32 v28, v79, v4
	v_add_f32_e32 v8, v43, v8
	v_exp_f32_e32 v47, v28
	v_sub_f32_e32 v28, v80, v4
	v_add_f32_e32 v8, v44, v8
	v_exp_f32_e32 v48, v28
	v_sub_f32_e32 v28, v81, v4
	v_add_f32_e32 v8, v45, v8
	v_exp_f32_e32 v49, v28
	v_sub_f32_e32 v28, v82, v4
	v_add_f32_e32 v8, v46, v8
	v_exp_f32_e32 v50, v28
	v_sub_f32_e32 v28, v83, v4
	v_add_f32_e32 v8, v47, v8
	v_exp_f32_e32 v51, v28
	v_sub_f32_e32 v28, v84, v4
	v_add_f32_e32 v8, v48, v8
	v_exp_f32_e32 v64, v28
	v_sub_f32_e32 v28, v85, v4
	v_add_f32_e32 v8, v49, v8
	v_exp_f32_e32 v65, v28
	v_sub_f32_e32 v28, v86, v4
	v_add_f32_e32 v8, v50, v8
	v_exp_f32_e32 v66, v28
	v_sub_f32_e32 v28, v87, v4
	v_add_f32_e32 v8, v51, v8
	v_exp_f32_e32 v67, v28
	v_sub_f32_e32 v28, v88, v4
	v_add_f32_e32 v8, v64, v8
	v_exp_f32_e32 v68, v28
	v_sub_f32_e32 v28, v89, v4
	v_add_f32_e32 v8, v65, v8
	v_exp_f32_e32 v69, v28
	v_sub_f32_e32 v28, v90, v4
	v_add_f32_e32 v8, v66, v8
	v_exp_f32_e32 v70, v28
	v_sub_f32_e32 v28, v91, v4
	v_add_f32_e32 v8, v67, v8
	v_exp_f32_e32 v71, v28
	v_sub_f32_e32 v28, v92, v4
	v_add_f32_e32 v8, v68, v8
	v_exp_f32_e32 v72, v28
	v_sub_f32_e32 v28, v93, v4
	v_add_f32_e32 v8, v69, v8
	v_exp_f32_e32 v73, v28
	v_sub_f32_e32 v28, v94, v4
	v_add_f32_e32 v8, v70, v8
	v_exp_f32_e32 v74, v28
	v_sub_f32_e32 v28, v95, v4
	v_add_f32_e32 v8, v71, v8
	v_exp_f32_e32 v75, v28
	v_sub_f32_e32 v28, v96, v4
	v_add_f32_e32 v8, v72, v8
	v_exp_f32_e32 v76, v28
	v_sub_f32_e32 v28, v97, v4
	v_add_f32_e32 v8, v73, v8
	v_exp_f32_e32 v77, v28
	v_sub_f32_e32 v28, v98, v4
	v_add_f32_e32 v8, v74, v8
	v_exp_f32_e32 v78, v28
	v_sub_f32_e32 v28, v99, v4
	v_add_f32_e32 v8, v75, v8
	v_exp_f32_e32 v79, v28
	v_sub_f32_e32 v28, v100, v4
	v_add_f32_e32 v8, v76, v8
	v_exp_f32_e32 v117, v28
	v_sub_f32_e32 v28, v101, v4
	v_add_f32_e32 v8, v77, v8
	v_exp_f32_e32 v154, v28
	v_sub_f32_e32 v28, v102, v4
	v_add_f32_e32 v8, v78, v8
	v_exp_f32_e32 v155, v28
; #define LAS __attribute__((address_space(3)))
; __device__ __forceinline__ unsigned pk2(float lo, float hi) { const f32x2 v = {lo, hi}; return __builtin_bit_cast(unsigned, __builtin_convertvector(v, bf16x2_t)); }
; #define BAR_LDS() do { asm volatile("s_waitcnt lgkmcnt(0)" ::: "memory"); __builtin_amdgcn_s_barrier(); asm volatile("" ::: "memory"); } while (0)
; #define XA_PUT_V() do { _Pragma("unroll") for (int i = 0; i < 4; ++i) { const int cidx = tid + 512 * i, r = cidx >> 3, c8 = cidx & 7; *(LAS u32x2*)(Vs + r * VS + c8 * 8) = (u32x2){stg[i].x, stg[i].y}; *(LAS u32x2*)(Vs + r * VS + c8 * 8 + 4) = (u32x2){stg[i].z, stg[i].w}; } } while (0)
; __device__ __forceinline__ void xattn_phase(KA a, LAS unsigned char* lds, int G, const int tid, const int bid) {
;     ...
;         float sum = 0.f;
; #pragma unroll
;         for (int n = 0; n < 16; ++n)
; #pragma unroll
;             for (int i = 0; i < 4; ++i) { const float p = __builtin_amdgcn_exp2f(accS[n][i] - mx); accS[n][i] = p; sum += p; }
;         sum += __shfl_xor(sum, 16); sum += __shfl_xor(sum, 32);
;         const float inv = __builtin_amdgcn_rcpf(sum);
;         bf16x8 pf[8];
; #pragma unroll
;         for (int kb = 0; kb < 8; ++kb) { u32x4 w; w.x = pk2(accS[2 * kb][0], accS[2 * kb][1]); w.y = pk2(accS[2 * kb][2], accS[2 * kb][3]); w.z = pk2(accS[2 * kb + 1][0], accS[2 * kb + 1][1]); w.w = pk2(accS[2 * kb + 1][2], accS[2 * kb + 1][3]); pf[kb] = __builtin_bit_cast(bf16x8, w); }
;         f32x4 accO[16];
; #pragma unroll
;         for (int n = 0; n < 16; ++n) accO[n] = (f32x4){0.f, 0.f, 0.f, 0.f};
;         const int un = u + G;
; #pragma unroll
;         for (int k4 = 0; k4 < 4; ++k4) {
;             BAR_LDS();
;             XA_PUT_V();
;             if (k4 < 3) XA_FETCH(u, 5 + k4); else if (un < 2560) XA_FETCH(un, 0);
;             BAR_LDS();
; #pragma unroll
;             for (int kb = 0; kb < 2; ++kb)
; #pragma unroll
;                 for (int dtile = 0; dtile < 16; ++dtile) {
;                     const u32x2 lo = *(const LAS u32x2*)(Vs + (16 * dtile + fr) * VS + 32 * kb + 4 * fq), hi = *(const LAS u32x2*)(Vs + (16 * dtile + fr) * VS + 32 * kb + 16 + 4 * fq);
;                     accO[dtile] = __builtin_amdgcn_mfma_f32_16x16x32_bf16(mk8(lo, hi), pf[k4 * 2 + kb], accO[dtile], 0, 0, 0);
;                 }
	v_sub_f32_e32 v28, v103, v4
	v_add_f32_e32 v8, v79, v8
	v_exp_f32_e32 v156, v28
	v_sub_f32_e32 v28, v104, v4
	v_add_f32_e32 v8, v117, v8
	v_exp_f32_e32 v157, v28
	v_sub_f32_e32 v28, v105, v4
	v_add_f32_e32 v8, v154, v8
	v_exp_f32_e32 v158, v28
	v_sub_f32_e32 v28, v106, v4
	v_add_f32_e32 v8, v155, v8
	v_exp_f32_e32 v159, v28
	v_sub_f32_e32 v28, v107, v4
	v_add_f32_e32 v8, v156, v8
	v_exp_f32_e32 v182, v28
	v_sub_f32_e32 v28, v108, v4
	v_add_f32_e32 v8, v157, v8
	v_exp_f32_e32 v183, v28
	v_sub_f32_e32 v28, v109, v4
	v_add_f32_e32 v8, v158, v8
	v_exp_f32_e32 v184, v28
	v_sub_f32_e32 v28, v110, v4
	v_add_f32_e32 v8, v159, v8
	v_exp_f32_e32 v185, v28
	v_sub_f32_e32 v28, v111, v4
	v_add_f32_e32 v8, v182, v8
	v_exp_f32_e32 v186, v28
	v_sub_f32_e32 v0, v0, v4
	v_add_f32_e32 v8, v183, v8
	v_exp_f32_e32 v187, v0
	v_cvt_pk_bf16_f32 v31, v14, v15
	v_cvt_pk_bf16_f32 v14, v40, v41
	v_mov_b64_e32 v[40:41], s[10:11]
	v_add_f32_e32 v8, v184, v8
	v_cvt_pk_bf16_f32 v30, v12, v13
	v_cvt_pk_bf16_f32 v20, v20, v21
	v_cvt_pk_bf16_f32 v21, v22, v23
	v_cvt_pk_bf16_f32 v22, v32, v33
	v_cvt_pk_bf16_f32 v12, v36, v37
	v_mad_i64_i32 v[24:25], s[10:11], v115, s24, v[40:41]
	v_mov_b32_e32 v115, v19
	v_mad_i64_i32 v[32:33], s[10:11], v122, s24, v[40:41]
	v_mad_i64_i32 v[36:37], s[10:11], v124, s24, v[40:41]
	v_mad_i64_i32 v[40:41], s[10:11], v126, s24, v[40:41]
	v_add_f32_e32 v8, v185, v8
	v_lshl_add_u64 v[120:121], v[24:25], 0, v[114:115]
	v_lshl_add_u64 v[122:123], v[32:33], 0, v[114:115]
	v_lshl_add_u64 v[124:125], v[36:37], 0, v[114:115]
	v_lshl_add_u64 v[126:127], v[40:41], 0, v[114:115]
	v_add_f32_e32 v8, v186, v8
	v_cvt_pk_bf16_f32 v23, v34, v35
	v_cvt_pk_bf16_f32 v13, v38, v39
	v_cvt_pk_bf16_f32 v15, v42, v43
	global_load_dwordx4 v[24:27], v[120:121], off offset:128
	global_load_dwordx4 v[32:35], v[122:123], off offset:128
	global_load_dwordx4 v[36:39], v[124:125], off offset:128
	global_load_dwordx4 v[40:43], v[126:127], off offset:128
	s_waitcnt lgkmcnt(0)
	s_barrier
	v_add_u32_e32 v115, 0x8000, v139
	v_add_f32_e32 v0, v187, v8
	v_cvt_pk_bf16_f32 v28, v7, v9
	v_cvt_pk_bf16_f32 v8, v44, v45
	v_cvt_pk_bf16_f32 v9, v46, v47
	ds_read2_b64 v[44:47], v115 offset0:128 offset1:132
	v_cvt_pk_bf16_f32 v29, v10, v11
	v_sub_f32_e32 v1, v1, v4
	v_exp_f32_e32 v188, v1
	s_waitcnt lgkmcnt(0)
	v_mfma_f32_16x16x32_bf16 v[52:55], v[44:47], v[28:31], 0
	ds_read2_b64 v[44:47], v193 offset0:128 offset1:132
	v_sub_f32_e32 v1, v2, v4
	v_exp_f32_e32 v189, v1
	s_waitcnt lgkmcnt(0)
	v_mfma_f32_16x16x32_bf16 v[56:59], v[44:47], v[28:31], 0
	ds_read2_b64 v[44:47], v194 offset0:128 offset1:132
	v_sub_f32_e32 v1, v3, v4
	v_exp_f32_e32 v190, v1
	s_waitcnt lgkmcnt(0)
	v_mfma_f32_16x16x32_bf16 v[60:63], v[44:47], v[28:31], 0
	ds_read2_b64 v[44:47], v195 offset0:128 offset1:132
	v_add_f32_e32 v0, v188, v0
	v_add_f32_e32 v0, v189, v0
	v_add_f32_e32 v0, v190, v0
	ds_bpermute_b32 v1, v5, v0
	v_cvt_pk_bf16_f32 v4, v64, v65
	v_cvt_pk_bf16_f32 v5, v66, v67
	s_waitcnt lgkmcnt(1)
	v_mfma_f32_16x16x32_bf16 v[64:67], v[44:47], v[28:31], 0
	ds_read2_b64 v[44:47], v196 offset0:192 offset1:196
	s_waitcnt lgkmcnt(1)
	v_add_f32_e32 v191, v0, v1
	ds_bpermute_b32 v192, v6, v191
	v_cvt_pk_bf16_f32 v6, v68, v69
	v_cvt_pk_bf16_f32 v7, v70, v71
	s_waitcnt lgkmcnt(1)
	v_mfma_f32_16x16x32_bf16 v[68:71], v[44:47], v[28:31], 0
	ds_read2_b64 v[44:47], v197 offset0:208 offset1:212
	v_cvt_pk_bf16_f32 v0, v72, v73
	v_cvt_pk_bf16_f32 v1, v74, v75
	s_waitcnt lgkmcnt(0)
	v_mfma_f32_16x16x32_bf16 v[72:75], v[44:47], v[28:31], 0
	ds_read2_b64 v[44:47], v198 offset0:224 offset1:228
	v_cvt_pk_bf16_f32 v2, v76, v77
	v_cvt_pk_bf16_f32 v3, v78, v79
	s_waitcnt lgkmcnt(0)
	v_mfma_f32_16x16x32_bf16 v[76:79], v[44:47], v[28:31], 0
	ds_read2_b64 v[44:47], v199 offset0:240 offset1:244
	v_cvt_pk_bf16_f32 v10, v48, v49
	v_cvt_pk_bf16_f32 v11, v50, v51
	s_waitcnt lgkmcnt(0)
	v_mfma_f32_16x16x32_bf16 v[80:83], v[44:47], v[28:31], 0
	ds_read2_b64 v[44:47], v200 offset1:4
	ds_read2_b64 v[48:51], v206 offset0:96 offset1:100
	ds_read2_b64 v[104:107], v143 offset1:4
	s_waitcnt lgkmcnt(2)
	v_mfma_f32_16x16x32_bf16 v[84:87], v[44:47], v[28:31], 0
	ds_read2_b64 v[44:47], v201 offset0:16 offset1:20
	s_mov_b64 s[10:11], -1
	s_waitcnt lgkmcnt(0)
	v_mfma_f32_16x16x32_bf16 v[88:91], v[44:47], v[28:31], 0
	ds_read2_b64 v[44:47], v202 offset0:32 offset1:36
	s_waitcnt lgkmcnt(0)
	v_mfma_f32_16x16x32_bf16 v[92:95], v[44:47], v[28:31], 0
	ds_read2_b64 v[44:47], v203 offset0:48 offset1:52
	s_waitcnt lgkmcnt(0)
	v_mfma_f32_16x16x32_bf16 v[96:99], v[44:47], v[28:31], 0
	ds_read2_b64 v[44:47], v204 offset0:64 offset1:68
	s_waitcnt lgkmcnt(0)
	v_mfma_f32_16x16x32_bf16 v[100:103], v[44:47], v[28:31], 0
	ds_read2_b64 v[44:47], v205 offset0:80 offset1:84
	s_waitcnt lgkmcnt(0)
	v_mfma_f32_16x16x32_bf16 v[44:47], v[44:47], v[28:31], 0
	v_mfma_f32_16x16x32_bf16 v[48:51], v[48:51], v[28:31], 0
	v_mfma_f32_16x16x32_bf16 v[28:31], v[104:107], v[28:31], 0
	ds_read2_b64 v[104:107], v115 offset0:136 offset1:140
	s_waitcnt lgkmcnt(0)
	v_mfma_f32_16x16x32_bf16 v[52:55], v[104:107], v[20:23], v[52:55]
	ds_read2_b64 v[104:107], v193 offset0:136 offset1:140
	s_waitcnt lgkmcnt(0)
	v_mfma_f32_16x16x32_bf16 v[56:59], v[104:107], v[20:23], v[56:59]
	ds_read2_b64 v[104:107], v194 offset0:136 offset1:140
	s_waitcnt lgkmcnt(0)
	v_mfma_f32_16x16x32_bf16 v[60:63], v[104:107], v[20:23], v[60:63]
	ds_read2_b64 v[104:107], v195 offset0:136 offset1:140
	s_waitcnt lgkmcnt(0)
	v_mfma_f32_16x16x32_bf16 v[64:67], v[104:107], v[20:23], v[64:67]
	ds_read2_b64 v[104:107], v196 offset0:200 offset1:204
	s_waitcnt lgkmcnt(0)
	v_mfma_f32_16x16x32_bf16 v[68:71], v[104:107], v[20:23], v[68:71]
	ds_read2_b64 v[104:107], v197 offset0:216 offset1:220
	s_waitcnt lgkmcnt(0)
; #define LAS __attribute__((address_space(3)))
; #define BAR_LDS() do { asm volatile("s_waitcnt lgkmcnt(0)" ::: "memory"); __builtin_amdgcn_s_barrier(); asm volatile("" ::: "memory"); } while (0)
; #define XA_PUT_V() do { _Pragma("unroll") for (int i = 0; i < 4; ++i) { const int cidx = tid + 512 * i, r = cidx >> 3, c8 = cidx & 7; *(LAS u32x2*)(Vs + r * VS + c8 * 8) = (u32x2){stg[i].x, stg[i].y}; *(LAS u32x2*)(Vs + r * VS + c8 * 8 + 4) = (u32x2){stg[i].z, stg[i].w}; } } while (0)
; __device__ __forceinline__ void xattn_phase(KA a, LAS unsigned char* lds, int G, const int tid, const int bid) {
;     ...
;         for (int k4 = 0; k4 < 4; ++k4) {
;             BAR_LDS();
;             XA_PUT_V();
;             if (k4 < 3) XA_FETCH(u, 5 + k4); else if (un < 2560) XA_FETCH(un, 0);
;             BAR_LDS();
; #pragma unroll
;             for (int kb = 0; kb < 2; ++kb)
; #pragma unroll
;                 for (int dtile = 0; dtile < 16; ++dtile) {
;                     const u32x2 lo = *(const LAS u32x2*)(Vs + (16 * dtile + fr) * VS + 32 * kb + 4 * fq), hi = *(const LAS u32x2*)(Vs + (16 * dtile + fr) * VS + 32 * kb + 16 + 4 * fq);
;                     accO[dtile] = __builtin_amdgcn_mfma_f32_16x16x32_bf16(mk8(lo, hi), pf[k4 * 2 + kb], accO[dtile], 0, 0, 0);
;                 }
	v_mfma_f32_16x16x32_bf16 v[72:75], v[104:107], v[20:23], v[72:75]
	ds_read2_b64 v[104:107], v198 offset0:232 offset1:236
	s_waitcnt lgkmcnt(0)
	v_mfma_f32_16x16x32_bf16 v[76:79], v[104:107], v[20:23], v[76:79]
	ds_read2_b64 v[104:107], v199 offset0:248 offset1:252
	s_waitcnt lgkmcnt(0)
	v_mfma_f32_16x16x32_bf16 v[80:83], v[104:107], v[20:23], v[80:83]
	ds_read2_b64 v[104:107], v200 offset0:8 offset1:12
	s_waitcnt lgkmcnt(0)
	v_mfma_f32_16x16x32_bf16 v[84:87], v[104:107], v[20:23], v[84:87]
	ds_read2_b64 v[104:107], v201 offset0:24 offset1:28
	s_waitcnt lgkmcnt(0)
	v_mfma_f32_16x16x32_bf16 v[88:91], v[104:107], v[20:23], v[88:91]
	ds_read2_b64 v[104:107], v202 offset0:40 offset1:44
	s_waitcnt lgkmcnt(0)
	v_mfma_f32_16x16x32_bf16 v[92:95], v[104:107], v[20:23], v[92:95]
	ds_read2_b64 v[104:107], v203 offset0:56 offset1:60
	s_waitcnt lgkmcnt(0)
	v_mfma_f32_16x16x32_bf16 v[96:99], v[104:107], v[20:23], v[96:99]
	ds_read2_b64 v[104:107], v204 offset0:72 offset1:76
	s_waitcnt lgkmcnt(0)
	v_mfma_f32_16x16x32_bf16 v[100:103], v[104:107], v[20:23], v[100:103]
	ds_read2_b64 v[104:107], v205 offset0:88 offset1:92
	s_waitcnt lgkmcnt(0)
	v_mfma_f32_16x16x32_bf16 v[108:111], v[104:107], v[20:23], v[44:47]
	s_nop 2
	ds_read2_b64 v[44:47], v206 offset0:104 offset1:108
	s_waitcnt lgkmcnt(0)
	v_mfma_f32_16x16x32_bf16 v[104:107], v[44:47], v[20:23], v[48:51]
	ds_read2_b64 v[44:47], v144 offset1:4
	s_waitcnt lgkmcnt(0)
	s_barrier
	s_waitcnt vmcnt(0)
	ds_write2_b64 v150, v[40:41], v[42:43] offset1:1
	ds_write2_b64 v151, v[36:37], v[38:39] offset1:1
	ds_write2_b64 v152, v[32:33], v[34:35] offset1:1
	ds_write2_b64 v153, v[24:25], v[26:27] offset1:1
	s_waitcnt lgkmcnt(4)
	v_mfma_f32_16x16x32_bf16 v[44:47], v[44:47], v[20:23], v[28:31]
	global_load_dwordx4 v[20:23], v[120:121], off offset:256
	global_load_dwordx4 v[24:27], v[122:123], off offset:256
	s_nop 0
	global_load_dwordx4 v[28:31], v[124:125], off offset:256
	global_load_dwordx4 v[32:35], v[126:127], off offset:256
	s_waitcnt lgkmcnt(0)
	s_barrier
	ds_read2_b64 v[244:247], v115 offset0:128 offset1:132
	ds_read2_b64 v[248:251], v193 offset0:128 offset1:132
	ds_read2_b64 v[208:211], v194 offset0:128 offset1:132
	ds_read2_b64 v[212:215], v195 offset0:128 offset1:132
	ds_read2_b64 v[216:219], v196 offset0:192 offset1:196
	ds_read2_b64 v[220:223], v197 offset0:208 offset1:212
	ds_read2_b64 v[224:227], v198 offset0:224 offset1:228
	s_waitcnt lgkmcnt(6)
	v_mfma_f32_16x16x32_bf16 v[48:51], v[244:247], v[12:15], v[52:55]
	ds_read2_b64 v[228:231], v199 offset0:240 offset1:244
	s_waitcnt lgkmcnt(6)
	v_mfma_f32_16x16x32_bf16 v[52:55], v[248:251], v[12:15], v[56:59]
	ds_read2_b64 v[232:235], v200 offset1:4
	s_waitcnt lgkmcnt(6)
	v_mfma_f32_16x16x32_bf16 v[56:59], v[208:211], v[12:15], v[60:63]
	ds_read2_b64 v[236:239], v201 offset0:16 offset1:20
	s_waitcnt lgkmcnt(6)
	v_mfma_f32_16x16x32_bf16 v[60:63], v[212:215], v[12:15], v[64:67]
	ds_read2_b64 v[240:243], v202 offset0:32 offset1:36
	s_waitcnt lgkmcnt(6)
	v_mfma_f32_16x16x32_bf16 v[64:67], v[216:219], v[12:15], v[68:71]
	ds_read2_b64 v[244:247], v203 offset0:48 offset1:52
	s_waitcnt lgkmcnt(6)
	v_mfma_f32_16x16x32_bf16 v[68:71], v[220:223], v[12:15], v[72:75]
	ds_read2_b64 v[248:251], v204 offset0:64 offset1:68
	s_waitcnt lgkmcnt(6)
	v_mfma_f32_16x16x32_bf16 v[72:75], v[224:227], v[12:15], v[76:79]
	ds_read2_b64 v[208:211], v205 offset0:80 offset1:84
	s_waitcnt lgkmcnt(6)
	v_mfma_f32_16x16x32_bf16 v[76:79], v[228:231], v[12:15], v[80:83]
	ds_read2_b64 v[212:215], v206 offset0:96 offset1:100
	s_waitcnt lgkmcnt(6)
	v_mfma_f32_16x16x32_bf16 v[80:83], v[232:235], v[12:15], v[84:87]
	ds_read2_b64 v[216:219], v143 offset1:4
	s_waitcnt lgkmcnt(6)
	v_mfma_f32_16x16x32_bf16 v[84:87], v[236:239], v[12:15], v[88:91]
	ds_read2_b64 v[220:223], v115 offset0:136 offset1:140
	s_waitcnt lgkmcnt(6)
	v_mfma_f32_16x16x32_bf16 v[88:91], v[240:243], v[12:15], v[92:95]
	ds_read2_b64 v[224:227], v193 offset0:136 offset1:140
	s_waitcnt lgkmcnt(6)
	v_mfma_f32_16x16x32_bf16 v[92:95], v[244:247], v[12:15], v[96:99]
	ds_read2_b64 v[228:231], v194 offset0:136 offset1:140
	s_waitcnt lgkmcnt(6)
	v_mfma_f32_16x16x32_bf16 v[96:99], v[248:251], v[12:15], v[100:103]
	s_nop 1
	ds_read2_b64 v[232:235], v195 offset0:136 offset1:140
	s_waitcnt lgkmcnt(6)
	v_mfma_f32_16x16x32_bf16 v[36:39], v[208:211], v[12:15], v[108:111]
	ds_read2_b64 v[236:239], v196 offset0:200 offset1:204
	s_waitcnt lgkmcnt(6)
	v_mfma_f32_16x16x32_bf16 v[40:43], v[212:215], v[12:15], v[104:107]
	ds_read2_b64 v[240:243], v197 offset0:216 offset1:220
	s_waitcnt lgkmcnt(6)
	v_mfma_f32_16x16x32_bf16 v[12:15], v[216:219], v[12:15], v[44:47]
	s_nop 2
	ds_read2_b64 v[244:247], v198 offset0:232 offset1:236
	s_waitcnt lgkmcnt(6)
	v_mfma_f32_16x16x32_bf16 v[44:47], v[220:223], v[8:11], v[48:51]
	s_nop 2
	ds_read2_b64 v[248:251], v199 offset0:248 offset1:252
	s_waitcnt lgkmcnt(6)
	v_mfma_f32_16x16x32_bf16 v[48:51], v[224:227], v[8:11], v[52:55]
	s_nop 2
	ds_read2_b64 v[208:211], v200 offset0:8 offset1:12
	s_waitcnt lgkmcnt(6)
	v_mfma_f32_16x16x32_bf16 v[52:55], v[228:231], v[8:11], v[56:59]
	s_nop 2
	ds_read2_b64 v[212:215], v201 offset0:24 offset1:28
	s_waitcnt lgkmcnt(6)
	v_mfma_f32_16x16x32_bf16 v[56:59], v[232:235], v[8:11], v[60:63]
	s_nop 2
	ds_read2_b64 v[216:219], v202 offset0:40 offset1:44
	s_waitcnt lgkmcnt(6)
	v_mfma_f32_16x16x32_bf16 v[60:63], v[236:239], v[8:11], v[64:67]
	s_nop 2
	ds_read2_b64 v[220:223], v203 offset0:56 offset1:60
	s_waitcnt lgkmcnt(6)
	v_mfma_f32_16x16x32_bf16 v[64:67], v[240:243], v[8:11], v[68:71]
	s_nop 2
	ds_read2_b64 v[224:227], v204 offset0:72 offset1:76
	s_waitcnt lgkmcnt(6)
	v_mfma_f32_16x16x32_bf16 v[68:71], v[244:247], v[8:11], v[72:75]
	s_nop 2
	ds_read2_b64 v[228:231], v205 offset0:88 offset1:92
	s_waitcnt lgkmcnt(6)
	v_mfma_f32_16x16x32_bf16 v[72:75], v[248:251], v[8:11], v[76:79]
	s_nop 2
	ds_read2_b64 v[232:235], v206 offset0:104 offset1:108
	s_waitcnt lgkmcnt(6)
	v_mfma_f32_16x16x32_bf16 v[76:79], v[208:211], v[8:11], v[80:83]
	s_nop 2
	s_waitcnt lgkmcnt(5)
	v_mfma_f32_16x16x32_bf16 v[80:83], v[212:215], v[8:11], v[84:87]
	s_nop 2
	s_waitcnt lgkmcnt(4)
	v_mfma_f32_16x16x32_bf16 v[84:87], v[216:219], v[8:11], v[88:91]
	s_nop 2
	s_waitcnt lgkmcnt(3)
	v_mfma_f32_16x16x32_bf16 v[88:91], v[220:223], v[8:11], v[92:95]
	s_nop 2
	s_waitcnt lgkmcnt(2)
	v_mfma_f32_16x16x32_bf16 v[92:95], v[224:227], v[8:11], v[96:99]
	s_nop 2
	s_waitcnt lgkmcnt(1)
	v_mfma_f32_16x16x32_bf16 v[100:103], v[228:231], v[8:11], v[36:39]
	s_nop 2
	s_waitcnt lgkmcnt(0)
	v_mfma_f32_16x16x32_bf16 v[96:99], v[232:235], v[8:11], v[40:43]
	ds_read2_b64 v[236:239], v144 offset1:4
	s_waitcnt lgkmcnt(0)
	s_barrier
; #define LAS __attribute__((address_space(3)))
; #define BAR_LDS() do { asm volatile("s_waitcnt lgkmcnt(0)" ::: "memory"); __builtin_amdgcn_s_barrier(); asm volatile("" ::: "memory"); } while (0)
; #define XA_PUT_V() do { _Pragma("unroll") for (int i = 0; i < 4; ++i) { const int cidx = tid + 512 * i, r = cidx >> 3, c8 = cidx & 7; *(LAS u32x2*)(Vs + r * VS + c8 * 8) = (u32x2){stg[i].x, stg[i].y}; *(LAS u32x2*)(Vs + r * VS + c8 * 8 + 4) = (u32x2){stg[i].z, stg[i].w}; } } while (0)
; __device__ __forceinline__ void xattn_phase(KA a, LAS unsigned char* lds, int G, const int tid, const int bid) {
;     ...
;         for (int k4 = 0; k4 < 4; ++k4) {
;             BAR_LDS();
;             XA_PUT_V();
;             if (k4 < 3) XA_FETCH(u, 5 + k4); else if (un < 2560) XA_FETCH(un, 0);
;             BAR_LDS();
; #pragma unroll
;             for (int kb = 0; kb < 2; ++kb)
; #pragma unroll
;                 for (int dtile = 0; dtile < 16; ++dtile) {
;                     const u32x2 lo = *(const LAS u32x2*)(Vs + (16 * dtile + fr) * VS + 32 * kb + 4 * fq), hi = *(const LAS u32x2*)(Vs + (16 * dtile + fr) * VS + 32 * kb + 16 + 4 * fq);
;                     accO[dtile] = __builtin_amdgcn_mfma_f32_16x16x32_bf16(mk8(lo, hi), pf[k4 * 2 + kb], accO[dtile], 0, 0, 0);
;                 }
	s_waitcnt vmcnt(0)
	ds_write2_b64 v150, v[32:33], v[34:35] offset1:1
	ds_write2_b64 v151, v[28:29], v[30:31] offset1:1
	ds_write2_b64 v152, v[24:25], v[26:27] offset1:1
	ds_write2_b64 v153, v[20:21], v[22:23] offset1:1
	s_waitcnt lgkmcnt(4)
	v_mfma_f32_16x16x32_bf16 v[36:39], v[236:239], v[8:11], v[12:15]
	global_load_dwordx4 v[20:23], v[126:127], off offset:384
	global_load_dwordx4 v[24:27], v[124:125], off offset:384
	global_load_dwordx4 v[8:11], v[122:123], off offset:384
	global_load_dwordx4 v[12:15], v[120:121], off offset:384
	s_waitcnt lgkmcnt(0)
	s_barrier
	ds_read2_b64 v[240:243], v115 offset0:128 offset1:132
	ds_read2_b64 v[244:247], v194 offset0:128 offset1:132
	ds_read2_b64 v[248:251], v195 offset0:128 offset1:132
	ds_read2_b64 v[208:211], v193 offset0:128 offset1:132
	ds_read2_b64 v[212:215], v197 offset0:208 offset1:212
	ds_read2_b64 v[216:219], v198 offset0:224 offset1:228
	ds_read2_b64 v[220:223], v196 offset0:192 offset1:196
	s_waitcnt lgkmcnt(6)
	v_mfma_f32_16x16x32_bf16 v[28:31], v[240:243], v[4:7], v[44:47]
	s_nop 1
	ds_read2_b64 v[224:227], v200 offset1:4
	s_waitcnt lgkmcnt(6)
	v_mfma_f32_16x16x32_bf16 v[40:43], v[244:247], v[4:7], v[52:55]
	s_nop 2
	ds_read2_b64 v[228:231], v201 offset0:16 offset1:20
	s_waitcnt lgkmcnt(6)
	v_mfma_f32_16x16x32_bf16 v[44:47], v[248:251], v[4:7], v[56:59]
	s_nop 2
	ds_read2_b64 v[232:235], v199 offset0:240 offset1:244
	s_waitcnt lgkmcnt(6)
	v_mfma_f32_16x16x32_bf16 v[32:35], v[208:211], v[4:7], v[48:51]
	s_nop 2
	ds_read2_b64 v[236:239], v203 offset0:48 offset1:52
	s_waitcnt lgkmcnt(6)
	v_mfma_f32_16x16x32_bf16 v[52:55], v[212:215], v[4:7], v[64:67]
	ds_read2_b64 v[240:243], v204 offset0:64 offset1:68
	s_waitcnt lgkmcnt(6)
	v_mfma_f32_16x16x32_bf16 v[56:59], v[216:219], v[4:7], v[68:71]
	s_nop 0
	s_nop 0
	ds_read2_b64 v[244:247], v202 offset0:32 offset1:36
	s_waitcnt lgkmcnt(6)
	v_mfma_f32_16x16x32_bf16 v[48:51], v[220:223], v[4:7], v[60:63]
	s_nop 2
	ds_read2_b64 v[248:251], v205 offset0:80 offset1:84
	s_waitcnt lgkmcnt(6)
	v_mfma_f32_16x16x32_bf16 v[64:67], v[224:227], v[4:7], v[76:79]
	ds_read2_b64 v[208:211], v206 offset0:96 offset1:100
	s_waitcnt lgkmcnt(6)
	v_mfma_f32_16x16x32_bf16 v[68:71], v[228:231], v[4:7], v[80:83]
	s_nop 0
	s_nop 0
	ds_read2_b64 v[212:215], v143 offset1:4
	s_waitcnt lgkmcnt(6)
	v_mfma_f32_16x16x32_bf16 v[60:63], v[232:235], v[4:7], v[72:75]
	s_nop 2
	ds_read2_b64 v[216:219], v115 offset0:136 offset1:140
	s_waitcnt lgkmcnt(6)
	v_mfma_f32_16x16x32_bf16 v[76:79], v[236:239], v[4:7], v[88:91]
	ds_read2_b64 v[220:223], v193 offset0:136 offset1:140
	s_waitcnt lgkmcnt(6)
	v_mfma_f32_16x16x32_bf16 v[88:91], v[240:243], v[4:7], v[92:95]
	ds_read2_b64 v[224:227], v194 offset0:136 offset1:140
	s_waitcnt lgkmcnt(6)
	v_mfma_f32_16x16x32_bf16 v[72:75], v[244:247], v[4:7], v[84:87]
	ds_read2_b64 v[228:231], v196 offset0:200 offset1:204
	s_waitcnt lgkmcnt(6)
	v_mfma_f32_16x16x32_bf16 v[92:95], v[248:251], v[4:7], v[100:103]
	ds_read2_b64 v[232:235], v195 offset0:136 offset1:140
	s_waitcnt lgkmcnt(6)
	v_mfma_f32_16x16x32_bf16 v[80:83], v[208:211], v[4:7], v[96:99]
	ds_read2_b64 v[236:239], v198 offset0:232 offset1:236
	s_waitcnt lgkmcnt(6)
	v_mfma_f32_16x16x32_bf16 v[84:87], v[212:215], v[4:7], v[36:39]
	ds_read2_b64 v[240:243], v197 offset0:216 offset1:220
	s_waitcnt lgkmcnt(6)
	v_mfma_f32_16x16x32_bf16 v[4:7], v[216:219], v[0:3], v[28:31]
	s_nop 2
	ds_read2_b64 v[244:247], v200 offset0:8 offset1:12
	s_waitcnt lgkmcnt(6)
	v_mfma_f32_16x16x32_bf16 v[32:35], v[220:223], v[0:3], v[32:35]
	ds_read2_b64 v[248:251], v199 offset0:248 offset1:252
	s_waitcnt lgkmcnt(6)
	v_mfma_f32_16x16x32_bf16 v[28:31], v[224:227], v[0:3], v[40:43]
	s_nop 2
	ds_read2_b64 v[208:211], v202 offset0:40 offset1:44
	s_waitcnt lgkmcnt(6)
	v_mfma_f32_16x16x32_bf16 v[40:43], v[228:231], v[0:3], v[48:51]
	s_nop 2
	ds_read2_b64 v[212:215], v201 offset0:24 offset1:28
	s_waitcnt lgkmcnt(6)
	v_mfma_f32_16x16x32_bf16 v[36:39], v[232:235], v[0:3], v[44:47]
	s_nop 2
	ds_read2_b64 v[216:219], v204 offset0:72 offset1:76
	s_waitcnt lgkmcnt(6)
	v_mfma_f32_16x16x32_bf16 v[48:51], v[236:239], v[0:3], v[56:59]
	s_nop 2
	ds_read2_b64 v[220:223], v203 offset0:56 offset1:60
	s_waitcnt lgkmcnt(6)
	v_mfma_f32_16x16x32_bf16 v[44:47], v[240:243], v[0:3], v[52:55]
	s_nop 2
	ds_read2_b64 v[224:227], v206 offset0:104 offset1:108
	s_waitcnt lgkmcnt(6)
	v_mfma_f32_16x16x32_bf16 v[56:59], v[244:247], v[0:3], v[64:67]
	s_nop 2
	s_waitcnt lgkmcnt(5)
	v_mfma_f32_16x16x32_bf16 v[52:55], v[248:251], v[0:3], v[60:63]
	s_nop 2
	s_waitcnt lgkmcnt(4)
	v_mfma_f32_16x16x32_bf16 v[64:67], v[208:211], v[0:3], v[72:75]
	s_nop 2
	s_waitcnt lgkmcnt(3)
	v_mfma_f32_16x16x32_bf16 v[60:63], v[212:215], v[0:3], v[68:71]
	s_nop 2
	s_waitcnt lgkmcnt(2)
	v_mfma_f32_16x16x32_bf16 v[72:75], v[216:219], v[0:3], v[88:91]
	s_nop 2
	s_waitcnt lgkmcnt(1)
	v_mfma_f32_16x16x32_bf16 v[68:71], v[220:223], v[0:3], v[76:79]
	s_nop 2
	s_waitcnt lgkmcnt(0)
	v_mfma_f32_16x16x32_bf16 v[80:83], v[224:227], v[0:3], v[80:83]
	ds_read2_b64 v[228:231], v205 offset0:88 offset1:92
	ds_read2_b64 v[232:235], v144 offset1:4
	s_waitcnt lgkmcnt(0)
	s_barrier
	s_waitcnt lgkmcnt(1)
	v_mfma_f32_16x16x32_bf16 v[76:79], v[228:231], v[0:3], v[92:95]
	s_waitcnt vmcnt(3)
	ds_write2_b64 v150, v[20:21], v[22:23] offset1:1
	s_waitcnt vmcnt(2)
	ds_write2_b64 v151, v[24:25], v[26:27] offset1:1
	s_waitcnt vmcnt(1)
	ds_write2_b64 v152, v[8:9], v[10:11] offset1:1
	s_waitcnt vmcnt(0)
	ds_write2_b64 v153, v[12:13], v[14:15] offset1:1
	s_waitcnt lgkmcnt(4)
	v_mfma_f32_16x16x32_bf16 v[84:87], v[232:235], v[0:3], v[84:87]
	s_cbranch_scc1 .LBB0_116
	s_add_i32 s20, s19, s14
	s_add_i32 s21, s18, s15
	s_mov_b64 s[10:11], 0
